# v80 with the running max folded into the QK^T accumulator init (NEGM block as MFMA C operand; the 32 per-tile subtractions only on the rare rescale path)
# speedup vs baseline: 1.0167x; 1.0050x over previous
; DI unsigned pk2(float a, float b) { f32x2 f = {a, b}; bf16v2 r = __builtin_convertvector(f, bf16v2); return __builtin_bit_cast(unsigned, r); }
; #define VLD(dst, j, dt) do { LAS unsigned char* va_ = vb + (32 * (dt) + n) * VROW + (16 * (j) + 4 * g) * 2; const u32x2 lo_ = *(const LAS u32x2*)(va_), hi_ = *(const LAS u32x2*)(va_ + 16); dst = (u32x4){lo_.x, lo_.y, hi_.x, hi_.y}; } while (0)
; DI void attn_unit(LAS unsigned char* lds, int wid, int b, int h, int qb) {
;     ...
;             const float mnew = fmaxf(mrow, mx), alpha = __builtin_amdgcn_exp2f(mrow - mnew); mrow = mnew;
;             float ls = 0.f;
; #pragma unroll
;             for (int i = 0; i < 16; ++i) { s0[i] = __builtin_amdgcn_exp2f(s0[i] - mnew); s1[i] = __builtin_amdgcn_exp2f(s1[i] - mnew); ls += s0[i] + s1[i]; }
;             lrow = lrow * alpha + ls;
;             if (__builtin_amdgcn_ballot_w64(alpha != 1.f) != 0ull) {
; #pragma unroll
;                 for (int dt = 0; dt < 4; ++dt)
; #pragma unroll
;                     for (int i = 0; i < 16; ++i) o[dt][i] *= alpha;
;             }
;             bf16x8 pf[4];
; #pragma unroll
;             for (int jj = 0; jj < 2; ++jj) { u32x4 w0, w1;
;                 w0.x = pk2(s0[8 * jj + 0], s0[8 * jj + 1]); w0.y = pk2(s0[8 * jj + 2], s0[8 * jj + 3]); w0.z = pk2(s0[8 * jj + 4], s0[8 * jj + 5]); w0.w = pk2(s0[8 * jj + 6], s0[8 * jj + 7]);
;                 w1.x = pk2(s1[8 * jj + 0], s1[8 * jj + 1]); w1.y = pk2(s1[8 * jj + 2], s1[8 * jj + 3]); w1.z = pk2(s1[8 * jj + 4], s1[8 * jj + 5]); w1.w = pk2(s1[8 * jj + 6], s1[8 * jj + 7]);
;                 pf[jj] = __builtin_bit_cast(bf16x8, w0); pf[2 + jj] = __builtin_bit_cast(bf16x8, w1); }
; #pragma unroll
;             for (int j = 0; j < 4; ++j) {
;                 if (j < 3) {
; #pragma unroll
;                     for (int dt = 0; dt < 4; ++dt) VLD(vf[(j + 1) & 1][dt], j + 1, dt);
;                 }
; #pragma unroll
;                 for (int dt = 0; dt < 4; ++dt) o[dt] = __builtin_amdgcn_mfma_f32_32x32x16_bf16(__builtin_bit_cast(bf16x8, vf[j & 1][dt]), pf[j], o[dt], 0, 0, 0);
;                 __builtin_amdgcn_sched_barrier(0); }
.LBB0_1076:
	v_exp_f32_e32 v80, v80
	v_exp_f32_e32 v96, v96
	v_exp_f32_e32 v81, v81
	v_exp_f32_e32 v97, v97
	v_exp_f32_e32 v82, v82
	v_exp_f32_e32 v98, v98
	v_exp_f32_e32 v83, v83
	v_exp_f32_e32 v99, v99
	v_add_f32_e32 v119, v96, v80
	v_exp_f32_e32 v84, v84
	v_exp_f32_e32 v100, v100
	v_add_f32_e32 v119, 0, v119
	v_add_f32_e32 v120, v97, v81
	v_exp_f32_e32 v85, v85
	v_exp_f32_e32 v101, v101
	v_add_f32_e32 v119, v120, v119
	v_add_f32_e32 v120, v98, v82
	v_exp_f32_e32 v86, v86
	v_exp_f32_e32 v102, v102
	v_add_f32_e32 v119, v120, v119
	v_add_f32_e32 v120, v99, v83
	v_exp_f32_e32 v87, v87
	v_exp_f32_e32 v103, v103
	v_add_f32_e32 v119, v120, v119
	v_add_f32_e32 v120, v100, v84
	v_exp_f32_e32 v88, v88
	v_exp_f32_e32 v104, v104
	v_add_f32_e32 v119, v120, v119
	v_add_f32_e32 v120, v101, v85
	v_exp_f32_e32 v89, v89
	v_exp_f32_e32 v105, v105
	v_add_f32_e32 v119, v120, v119
	v_add_f32_e32 v120, v102, v86
	v_exp_f32_e32 v90, v90
	v_exp_f32_e32 v106, v106
	v_add_f32_e32 v119, v120, v119
	v_add_f32_e32 v120, v103, v87
	v_exp_f32_e32 v91, v91
	v_exp_f32_e32 v107, v107
	v_add_f32_e32 v119, v120, v119
	v_add_f32_e32 v120, v104, v88
	v_exp_f32_e32 v92, v92
	v_exp_f32_e32 v108, v108
	v_add_f32_e32 v119, v120, v119
	v_add_f32_e32 v120, v105, v89
	v_exp_f32_e32 v93, v93
	v_exp_f32_e32 v109, v109
	v_add_f32_e32 v119, v120, v119
	v_add_f32_e32 v120, v106, v90
	v_exp_f32_e32 v94, v94
	v_exp_f32_e32 v110, v110
	v_add_f32_e32 v119, v120, v119
	v_add_f32_e32 v120, v107, v91
	v_exp_f32_e32 v95, v95
	v_exp_f32_e32 v111, v111
	v_add_f32_e32 v119, v120, v119
	v_add_f32_e32 v120, v108, v92
	v_add_f32_e32 v119, v120, v119
	v_add_f32_e32 v120, v109, v93
	v_cvt_pk_bf16_f32 v80, v80, v81
	v_cvt_pk_bf16_f32 v81, v82, v83
	v_cvt_pk_bf16_f32 v82, v84, v85
	v_cvt_pk_bf16_f32 v83, v86, v87
	v_add_f32_e32 v119, v120, v119
	v_cvt_pk_bf16_f32 v86, v92, v93
	v_mfma_f32_32x32x16_bf16 v[64:79], v[2:5], v[80:83], v[64:79]
	v_add_f32_e32 v2, v110, v94
	v_add_f32_e32 v2, v2, v119
	v_add_f32_e32 v3, v111, v95
	v_add_f32_e32 v118, v3, v2
	v_cvt_pk_bf16_f32 v2, v96, v97
	v_cvt_pk_bf16_f32 v3, v98, v99
	v_cvt_pk_bf16_f32 v4, v100, v101
	s_waitcnt lgkmcnt(1)
	v_mfma_f32_32x32x16_bf16 v[48:63], v[112:115], v[80:83], v[48:63]
	v_cvt_pk_bf16_f32 v5, v102, v103
	v_cvt_pk_bf16_f32 v87, v94, v95
	v_fmac_f32_e32 v118, v185, v0
	v_cvt_pk_bf16_f32 v84, v88, v89
	v_cvt_pk_bf16_f32 v85, v90, v91
	v_cvt_pk_bf16_f32 v88, v104, v105
	v_cvt_pk_bf16_f32 v89, v106, v107
	v_mfma_f32_32x32x16_bf16 v[32:47], v[10:13], v[80:83], v[32:47]
	ds_read2_b64 v[10:13], v15 offset0:132 offset1:134
	ds_read2_b64 v[92:95], v116 offset0:164 offset1:166
	ds_read2_b64 v[96:99], v117 offset0:196 offset1:198
	ds_read2_b64 v[100:103], v14 offset0:228 offset1:230
	v_cvt_pk_bf16_f32 v90, v108, v109
	v_cvt_pk_bf16_f32 v91, v110, v111
	s_waitcnt lgkmcnt(4)
	v_mfma_f32_32x32x16_bf16 v[16:31], v[6:9], v[80:83], v[16:31]
	s_waitcnt lgkmcnt(3)
	v_mfma_f32_32x32x16_bf16 v[64:79], v[10:13], v[84:87], v[64:79]
	s_waitcnt lgkmcnt(2)
	v_mfma_f32_32x32x16_bf16 v[48:63], v[92:95], v[84:87], v[48:63]
	ds_read2_b64 v[6:9], v15 offset0:136 offset1:138
	ds_read2_b64 v[10:13], v116 offset0:168 offset1:170
	ds_read2_b64 v[80:83], v117 offset0:200 offset1:202
	ds_read2_b64 v[92:95], v14 offset0:232 offset1:234
	s_waitcnt lgkmcnt(5)
	v_mfma_f32_32x32x16_bf16 v[32:47], v[96:99], v[84:87], v[32:47]
	s_waitcnt lgkmcnt(4)
	v_mfma_f32_32x32x16_bf16 v[16:31], v[100:103], v[84:87], v[16:31]
	s_waitcnt lgkmcnt(3)
	v_mfma_f32_32x32x16_bf16 v[64:79], v[6:9], v[2:5], v[64:79]
	s_waitcnt lgkmcnt(2)
	v_mfma_f32_32x32x16_bf16 v[48:63], v[10:13], v[2:5], v[48:63]
	s_waitcnt lgkmcnt(1)
	v_mfma_f32_32x32x16_bf16 v[32:47], v[80:83], v[2:5], v[32:47]
	ds_read2_b64 v[6:9], v15 offset0:140 offset1:142
	ds_read2_b64 v[10:13], v116 offset0:172 offset1:174
	ds_read2_b64 v[80:83], v117 offset0:204 offset1:206
	ds_read2_b64 v[84:87], v14 offset0:236 offset1:238
	s_waitcnt lgkmcnt(4)
	v_mfma_f32_32x32x16_bf16 v[16:31], v[92:95], v[2:5], v[16:31]
	s_waitcnt lgkmcnt(3)
	v_mfma_f32_32x32x16_bf16 v[64:79], v[6:9], v[88:91], v[64:79]
	s_waitcnt lgkmcnt(2)
	v_mfma_f32_32x32x16_bf16 v[48:63], v[10:13], v[88:91], v[48:63]
	s_waitcnt lgkmcnt(1)
	v_mfma_f32_32x32x16_bf16 v[32:47], v[80:83], v[88:91], v[32:47]
	s_waitcnt lgkmcnt(0)
	v_mfma_f32_32x32x16_bf16 v[16:31], v[84:87], v[88:91], v[16:31]
	v_mov_b32_e32 v185, v118

; DI CP* kparams() { CP* kp = (CP*)__builtin_amdgcn_kernarg_segment_ptr(); asm volatile("" : "+s"(kp)); return kp; }
; DI int lane_id() { int l = __builtin_amdgcn_mbcnt_hi(-1, __builtin_amdgcn_mbcnt_lo(-1, 0)); asm volatile("" : "+v"(l)); return l; }
; #define A_LOAD(kt) do { const size_t ko = (size_t)(kt) * 64; st0 = *(const u32x4*)(kn_src + ko * 2048); st1 = *(const u32x4*)(kn_src + (ko + 32) * 2048); \
;         st2 = *(const u32x4*)(kr_src + ko * 64); st3 = *(const u32x4*)(v_src + ko); st4 = *(const u32x4*)(v_src + ko + (size_t)64 * 8192); } while (0)
; DI void attn_unit(LAS unsigned char* lds, int wid, int b, int h, int qb) {
;     CP& p = *kparams();
;     const int lane = lane_id(), tid = wid * 64 + lane, n = lane & 31, g = lane >> 5;
;     const int q0 = qb * 256 + wid * 32, cq = q0 >> 6, nkt = 4 * qb + 4;
;     const size_t tokq = (size_t)b * SEQ + q0 + n;
;     const bf16_t* Q = WSB(OFF_Q); const bf16_t* KN = WSB(OFF_KN); const bf16_t* KR = WSB(OFF_KR); const bf16_t* VT = WSB(OFF_VT2);
;     bf16x8 qf[12];
; #pragma unroll
;     for (int ks = 0; ks < 12; ++ks) qf[ks] = *(const bf16x8*)(Q + tokq * 3072 + h * 192 + ks * 16 + g * 8);
;     f32x16 o[4];
; #pragma unroll
;     for (int dt = 0; dt < 4; ++dt)
; #pragma unroll
;         for (int i = 0; i < 16; ++i) o[dt][i] = 0.f;
;     float mrow = -__builtin_inff(), lrow = 0.f;
;     const int krow = tid >> 4, kc16 = tid & 15, rrow = tid >> 3, rc8 = tid & 7;
;     const bf16_t* kn_src = KN + ((size_t)b * SEQ + krow) * 2048 + h * 128 + kc16 * 8;
;     const bf16_t* kr_src = KR + ((size_t)b * SEQ + rrow) * 64 + rc8 * 8;
;     const bf16_t* v_src = VT + ((size_t)h * 128 + rrow) * 8192 + (size_t)b * SEQ + rc8 * 8;
;     const int kn_dst = krow * KROW + kc16 * 16, kr_dst = rrow * KROW + 256 + rc8 * 16, v_dst = KBYTES + rrow * VROW + rc8 * 16;
;     u32x4 st0, st1, st2, st3, st4;
;     ...
;     A_LOAD(0); A_WRITE(0); __syncthreads();
.LBB0_1078:
	s_lshl_b32 s4, s55, 2
	s_and_b32 s4, s4, 28
	s_ashr_i32 s59, s55, 6
	s_mov_b64 s[16:17], s[0:1]
	v_mov_b32_e32 v183, v201
	s_add_i32 s4, s4, s59
	s_bfe_u32 s56, s55, 0x30003
	s_load_dwordx2 s[24:25], s[16:17], 0xa8
	s_ashr_i32 s22, s4, 4
	s_and_b32 s20, s4, 15
	s_xor_b32 s4, s56, 15
	s_lshl_b32 s18, s4, 8
	s_ashr_i32 s23, s22, 31
	s_lshr_b32 s57, s55, 3
	s_add_i32 s21, s18, s29
	s_lshl_b32 s61, s4, 2
	s_lshl_b64 s[16:17], s[22:23], 12
	v_and_b32_e32 v197, 31, v183
	s_add_u32 s26, s16, s21
	v_or_b32_e32 v0, s26, v197
	s_waitcnt lgkmcnt(0)
	v_mov_b64_e32 v[2:3], s[24:25]
	v_mad_u64_u32 v[2:3], s[18:19], v0, s37, v[2:3]
	v_add_u32_e32 v0, s28, v183
	v_ashrrev_i32_e32 v26, 3, v0
	v_ashrrev_i32_e32 v27, 31, v26
	s_addc_u32 s27, s17, 0
	s_mul_i32 s58, s20, 0xc0
	v_ashrrev_i32_e32 v24, 4, v0
	v_lshl_add_u64 v[4:5], s[16:17], 0, v[26:27]
	v_mad_i32_i24 v3, s27, v200, v3
	s_lshl_b32 s4, s58, 1
	v_ashrrev_i32_e32 v25, 31, v24
	v_lshlrev_b64 v[4:5], 7, v[4:5]
	v_lshlrev_b32_e32 v6, 4, v183
	v_lshl_add_u64 v[22:23], v[2:3], 0, s[4:5]
	v_lshl_add_u64 v[2:3], s[16:17], 0, v[24:25]
	s_lshl_b32 s4, s20, 7
	v_lshl_add_u64 v[4:5], s[24:25], 0, v[4:5]
	v_and_b32_e32 v28, 0x70, v6
	v_mov_b32_e32 v29, v1
	v_lshlrev_b64 v[2:3], 12, v[2:3]
	v_lshl_add_u64 v[10:11], v[4:5], 0, v[28:29]
	v_lshl_add_u64 v[4:5], v[26:27], 0, s[4:5]
	v_and_b32_e32 v32, 15, v183
	v_lshl_add_u64 v[2:3], s[24:25], 0, v[2:3]
	s_lshl_b32 s18, s20, 8
	s_mov_b32 s19, s5
	v_lshlrev_b64 v[4:5], 14, v[4:5]
	v_lshl_add_u64 v[2:3], v[2:3], 0, s[18:19]
	v_lshlrev_b32_e32 v0, 4, v32
	v_lshl_add_u64 v[4:5], s[24:25], 0, v[4:5]
	s_lshl_b64 s[18:19], s[22:23], 13
	v_lshl_add_u64 v[2:3], v[2:3], 0, v[0:1]
	v_lshl_add_u64 v[4:5], v[4:5], 0, s[18:19]
	v_lshl_add_u64 v[18:19], v[4:5], 0, v[28:29]
	v_add_co_u32_e32 v4, vcc, s40, v2
	v_ashrrev_i32_e32 v29, 5, v183
	s_nop 0
	v_addc_co_u32_e32 v5, vcc, 0, v3, vcc
	v_add_co_u32_e32 v6, vcc, s41, v2
	v_lshlrev_b32_e32 v184, 3, v29
	s_nop 0
	v_addc_co_u32_e32 v7, vcc, 0, v3, vcc
	v_add_co_u32_e32 v10, vcc, s42, v10
	v_ashrrev_i32_e32 v185, 31, v184
	s_nop 0
	v_addc_co_u32_e32 v11, vcc, 0, v11, vcc
	v_add_co_u32_e32 v14, vcc, s43, v18
	v_lshl_add_u64 v[22:23], v[184:185], 1, v[22:23]
	s_nop 0
	v_addc_co_u32_e32 v15, vcc, 0, v19, vcc
	v_add_co_u32_e32 v18, vcc, s44, v18
	global_load_dwordx4 v[2:5], v[4:5], off
	s_nop 0
	global_load_dwordx4 v[6:9], v[6:7], off
	v_addc_co_u32_e32 v19, vcc, 0, v19, vcc
	v_lshl_add_u64 v[30:31], v[22:23], 0, s[8:9]
	v_add_co_u32_e32 v22, vcc, s38, v22
	global_load_dwordx4 v[10:13], v[10:11], off
	s_nop 0
	v_addc_co_u32_e32 v23, vcc, 0, v23, vcc
	global_load_dwordx4 v[14:17], v[14:15], off
	s_lshr_b32 s62, s21, 6
	global_load_dwordx4 v[18:21], v[18:19], off
	s_nop 0
	global_load_dwordx4 v[138:141], v[30:31], off offset:32
	global_load_dwordx4 v[134:137], v[30:31], off offset:64
	global_load_dwordx4 v[130:133], v[30:31], off offset:96
	global_load_dwordx4 v[126:129], v[30:31], off offset:128
	global_load_dwordx4 v[122:125], v[30:31], off offset:160
	global_load_dwordx4 v[118:121], v[30:31], off offset:192
	global_load_dwordx4 v[114:117], v[30:31], off offset:224
	global_load_dwordx4 v[110:113], v[30:31], off offset:256
	global_load_dwordx4 v[106:109], v[30:31], off offset:288
	global_load_dwordx4 v[102:105], v[30:31], off offset:320
	global_load_dwordx4 v[142:145], v[22:23], off
	global_load_dwordx4 v[98:101], v[30:31], off offset:352
	v_mad_u64_u32 v[186:187], s[20:21], v24, s39, v[0:1]
	v_mad_u64_u32 v[188:189], s[20:21], v26, s39, v[28:29]
	v_add_u32_e32 v22, 0, v186
	s_and_b32 s20, s31, 12
	s_add_i32 s20, s20, s59
	s_and_b32 s60, s20, 15
	s_or_b32 s63, s61, 3
	s_waitcnt vmcnt(0)
	ds_write_b128 v22, v[2:5]
	ds_write_b128 v22, v[6:9] offset:12800
	v_add_u32_e32 v2, 0, v188
	v_mul_lo_u32 v3, v26, s45
	v_add_u32_e32 v198, v188, v3
	s_lshl_b32 s59, s60, 21
	s_add_u32 s20, s18, s59
	ds_write_b128 v2, v[10:13] offset:256
	v_add_u32_e32 v2, v2, v3
	v_add_u32_e32 v3, 0x6400, v2
	v_add_u32_e32 v2, 0x8600, v2
	ds_write2_b64 v3, v[14:15], v[16:17] offset1:1
	ds_write2_b64 v2, v[18:19], v[20:21] offset1:1
	v_lshlrev_b32_e32 v2, 2, v183
	v_xor_b32_e32 v185, 0x80, v2
	v_lshlrev_b64 v[2:3], 14, v[26:27]
	s_addc_u32 s21, s19, 0
	v_lshl_add_u64 v[190:191], s[20:21], 0, v[2:3]
	s_lshl_b64 s[20:21], s[22:23], 19
	s_add_u32 s20, s20, 0xe002000
	s_addc_u32 s21, s21, 0
	v_lshlrev_b64 v[2:3], 7, v[26:27]
	v_lshl_add_u64 v[192:193], s[20:21], 0, v[2:3]
	s_lshl_b64 s[22:23], s[22:23], 24
	v_lshlrev_b64 v[2:3], 12, v[24:25]
	v_mov_b32_e32 v16, v1
	v_mov_b32_e32 v17, v1
	v_lshlrev_b32_e32 v182, 3, v32
	v_lshlrev_b32_e32 v202, 4, v29
	v_or_b32_e32 v190, v190, v28
	v_or_b32_e32 v192, v192, v28
	v_lshl_add_u64 v[194:195], s[22:23], 0, v[2:3]
	s_lshl_b32 s60, s60, 8
	v_mov_b32_e32 v2, v1
	v_mov_b32_e32 v3, v1
	v_mov_b32_e32 v4, v1
	v_mov_b32_e32 v5, v1
	v_mov_b32_e32 v6, v1
	v_mov_b32_e32 v7, v1
	v_mov_b32_e32 v8, v1
	v_mov_b32_e32 v9, v1
	v_mov_b32_e32 v10, v1
	v_mov_b32_e32 v11, v1
	v_mov_b32_e32 v12, v1
	v_mov_b32_e32 v13, v1
	v_mov_b32_e32 v14, v1
	v_mov_b32_e32 v15, v1
	v_mov_b64_e32 v[32:33], v[16:17]
	v_mov_b64_e32 v[48:49], v[16:17]
	v_mov_b64_e32 v[64:65], v[16:17]
	v_mul_u32_u24_e32 v199, 0x190, v197
	v_mul_u32_u24_e32 v189, 0x88, v197
	v_or3_b32 v194, v194, s60, v0
	v_mov_b32_e32 v170, 0xff800000
	v_mov_b64_e32 v[30:31], v[14:15]
	v_mov_b64_e32 v[28:29], v[12:13]
	v_mov_b64_e32 v[26:27], v[10:11]
	v_mov_b64_e32 v[24:25], v[8:9]
	v_mov_b64_e32 v[22:23], v[6:7]
	v_mov_b64_e32 v[20:21], v[4:5]
	v_mov_b64_e32 v[18:19], v[2:3]
	v_mov_b64_e32 v[46:47], v[14:15]
	v_mov_b64_e32 v[44:45], v[12:13]
	v_mov_b64_e32 v[42:43], v[10:11]
	v_mov_b64_e32 v[40:41], v[8:9]
	v_mov_b64_e32 v[38:39], v[6:7]
	v_mov_b64_e32 v[36:37], v[4:5]
	v_mov_b64_e32 v[34:35], v[2:3]
	v_mov_b64_e32 v[62:63], v[14:15]
	v_mov_b64_e32 v[60:61], v[12:13]
	v_mov_b64_e32 v[58:59], v[10:11]
	v_mov_b64_e32 v[56:57], v[8:9]
	v_mov_b64_e32 v[54:55], v[6:7]
	v_mov_b64_e32 v[52:53], v[4:5]
	v_mov_b64_e32 v[50:51], v[2:3]
	v_mov_b32_e32 v187, 0
	s_mov_b32 s64, s5
	s_waitcnt lgkmcnt(0)
	s_barrier
	v_mov_b32_e32 v216, 0
	v_mov_b32_e32 v217, 0
	v_mov_b32_e32 v218, 0
	v_mov_b32_e32 v219, 0
	v_mov_b32_e32 v220, 0
	v_mov_b32_e32 v221, 0
	v_mov_b32_e32 v222, 0
	v_mov_b32_e32 v223, 0
	v_mov_b32_e32 v224, 0
	v_mov_b32_e32 v225, 0
	v_mov_b32_e32 v226, 0
	v_mov_b32_e32 v227, 0
	v_mov_b32_e32 v228, 0
	v_mov_b32_e32 v229, 0
	v_mov_b32_e32 v230, 0
	v_mov_b32_e32 v231, 0
	s_add_u32 s70, s24, 0x11140000
	s_addc_u32 s71, s25, 0
	s_add_u32 s72, s24, 0x11160000
	s_addc_u32 s73, s25, 0
	s_add_u32 s74, s24, 0x13100000
	s_addc_u32 s75, s25, 0
	s_add_u32 s76, s24, 0x13200000
	s_addc_u32 s77, s25, 0
	s_mov_b64 s[78:79], s[24:25]
; #define LAS __attribute__((address_space(3)))
; DI float shfl_xor_l(float v, int lane, int m) { return __int_as_float(__builtin_amdgcn_ds_bpermute((lane ^ m) << 2, __float_as_int(v))); }
; #define VLD(dst, j, dt) do { LAS unsigned char* va_ = vb + (32 * (dt) + n) * VROW + (16 * (j) + 4 * g) * 2; const u32x2 lo_ = *(const LAS u32x2*)(va_), hi_ = *(const LAS u32x2*)(va_ + 16); dst = (u32x4){lo_.x, lo_.y, hi_.x, hi_.y}; } while (0)
; DI void attn_unit(LAS unsigned char* lds, int wid, int b, int h, int qb) {
;     ...
;         if (kt <= cq) {
;             LAS unsigned char* kb = lds + buf * ABUF; LAS unsigned char* vb = kb + KBYTES;
;             f32x16 s0, s1;
; #pragma unroll
;             for (int i = 0; i < 16; ++i) { s0[i] = 0.f; s1[i] = 0.f; }
;     ...
;             bf16x8 ka[3][2];
;             ka[0][0] = KLD(0, 0); ka[0][1] = KLD(0, 1); ka[1][0] = KLD(1, 0); ka[1][1] = KLD(1, 1);
; #pragma unroll
;             for (int ks = 0; ks < 12; ++ks) {
;                 if (ks + 2 < 12) { ka[(ks + 2) % 3][0] = KLD(ks + 2, 0); ka[(ks + 2) % 3][1] = KLD(ks + 2, 1); }
;                 s0 = __builtin_amdgcn_mfma_f32_32x32x16_bf16(ka[ks % 3][0], qf[ks], s0, 0, 0, 0); s1 = __builtin_amdgcn_mfma_f32_32x32x16_bf16(ka[ks % 3][1], qf[ks], s1, 0, 0, 0);
;                 __builtin_amdgcn_sched_barrier(0); }
;             u32x4 vf[2][4];
; #pragma unroll
;             for (int dt = 0; dt < 4; ++dt) VLD(vf[0][dt], 0, dt);
;             float mx = s0[0];
; #pragma unroll
;             for (int i = 1; i < 16; ++i) mx = fmaxf(mx, s0[i]);
; #pragma unroll
;             for (int i = 0; i < 16; ++i) mx = fmaxf(mx, s1[i]);
;             mx = fmaxf(mx, shfl_xor_l(mx, lane, 32));
;             const float mnew = fmaxf(mrow, mx), alpha = __builtin_amdgcn_exp2f(mrow - mnew); mrow = mnew;
;             float ls = 0.f;
; #pragma unroll
;             for (int i = 0; i < 16; ++i) { s0[i] = __builtin_amdgcn_exp2f(s0[i] - mnew); s1[i] = __builtin_amdgcn_exp2f(s1[i] - mnew); ls += s0[i] + s1[i]; }
;             lrow = lrow * alpha + ls;
;             if (__builtin_amdgcn_ballot_w64(alpha != 1.f) != 0ull) {
.LBB0_1079:
	s_and_b32 s65, s64, 1
	global_load_dwordx4 v[146:149], v194, s[70:71]
	global_load_dwordx4 v[150:153], v194, s[72:73]
	global_load_dwordx4 v[154:157], v192, s[78:79]
	global_load_dwordx4 v[158:161], v190, s[74:75] offset:128
	global_load_dwordx4 v[162:165], v190, s[76:77] offset:128
	s_cmp_gt_u32 s64, s62
	s_cbranch_scc1 .LBB0_1083
	s_mul_i32 s66, s65, 0xa800
	s_add_i32 s66, s66, 0
	v_add3_u32 v171, s66, v199, v202
	ds_read_b128 v[66:69], v171
	ds_read_b128 v[166:169], v171 offset:32
	ds_read_b128 v[82:85], v171 offset:12800
	ds_read_b128 v[172:175], v171 offset:64
	ds_read_b128 v[176:179], v171 offset:12832
	ds_read_b128 v[204:207], v171 offset:12864
	s_waitcnt lgkmcnt(3)
	v_mfma_f32_32x32x16_bf16 v[82:97], v[82:85], v[142:145], v[216:231]
	v_mfma_f32_32x32x16_bf16 v[66:81], v[66:69], v[142:145], v[216:231]
	v_mfma_f32_32x32x16_bf16 v[66:81], v[166:169], v[138:141], v[66:81]
	ds_read_b128 v[166:169], v171 offset:96
	ds_read_b128 v[208:211], v171 offset:12896
	s_waitcnt lgkmcnt(3)
	v_mfma_f32_32x32x16_bf16 v[82:97], v[176:179], v[138:141], v[82:97]
	v_mfma_f32_32x32x16_bf16 v[66:81], v[172:175], v[134:137], v[66:81]
	ds_read_b128 v[172:175], v171 offset:128
	ds_read_b128 v[176:179], v171 offset:12928
	s_waitcnt lgkmcnt(4)
	v_mfma_f32_32x32x16_bf16 v[82:97], v[204:207], v[134:137], v[82:97]
	s_waitcnt lgkmcnt(3)
	v_mfma_f32_32x32x16_bf16 v[66:81], v[166:169], v[130:133], v[66:81]
	ds_read_b128 v[166:169], v171 offset:160
	ds_read_b128 v[204:207], v171 offset:12960
	s_waitcnt lgkmcnt(4)
	v_mfma_f32_32x32x16_bf16 v[82:97], v[208:211], v[130:133], v[82:97]
	s_waitcnt lgkmcnt(3)
	v_mfma_f32_32x32x16_bf16 v[66:81], v[172:175], v[126:129], v[66:81]
	ds_read_b128 v[172:175], v171 offset:192
	ds_read_b128 v[208:211], v171 offset:12992
	s_waitcnt lgkmcnt(4)
	v_mfma_f32_32x32x16_bf16 v[82:97], v[176:179], v[126:129], v[82:97]
	s_waitcnt lgkmcnt(3)
	v_mfma_f32_32x32x16_bf16 v[66:81], v[166:169], v[122:125], v[66:81]
	ds_read_b128 v[166:169], v171 offset:224
	ds_read_b128 v[176:179], v171 offset:13024
	s_waitcnt lgkmcnt(4)
	v_mfma_f32_32x32x16_bf16 v[82:97], v[204:207], v[122:125], v[82:97]
	s_waitcnt lgkmcnt(3)
	v_mfma_f32_32x32x16_bf16 v[66:81], v[172:175], v[118:121], v[66:81]
	ds_read_b128 v[172:175], v171 offset:256
	ds_read_b128 v[204:207], v171 offset:13056
	s_waitcnt lgkmcnt(4)
	v_mfma_f32_32x32x16_bf16 v[82:97], v[208:211], v[118:121], v[82:97]
	s_waitcnt lgkmcnt(3)
	v_mfma_f32_32x32x16_bf16 v[66:81], v[166:169], v[114:117], v[66:81]
	ds_read_b128 v[166:169], v171 offset:288
	ds_read_b128 v[208:211], v171 offset:13088
	s_waitcnt lgkmcnt(4)
	v_mfma_f32_32x32x16_bf16 v[82:97], v[176:179], v[114:117], v[82:97]
	s_waitcnt lgkmcnt(3)
	v_mfma_f32_32x32x16_bf16 v[66:81], v[172:175], v[110:113], v[66:81]
	ds_read_b128 v[172:175], v171 offset:320
	ds_read_b128 v[176:179], v171 offset:13120
	s_waitcnt lgkmcnt(4)
	v_mfma_f32_32x32x16_bf16 v[82:97], v[204:207], v[110:113], v[82:97]
	s_waitcnt lgkmcnt(3)
	v_mfma_f32_32x32x16_bf16 v[66:81], v[166:169], v[106:109], v[66:81]
	ds_read_b128 v[166:169], v171 offset:352
	ds_read_b128 v[212:215], v171 offset:13152
	s_waitcnt lgkmcnt(4)
	v_mfma_f32_32x32x16_bf16 v[82:97], v[208:211], v[106:109], v[82:97]
	s_waitcnt lgkmcnt(3)
	v_mfma_f32_32x32x16_bf16 v[66:81], v[172:175], v[102:105], v[66:81]
	s_waitcnt lgkmcnt(2)
	v_mfma_f32_32x32x16_bf16 v[82:97], v[176:179], v[102:105], v[82:97]
	s_waitcnt lgkmcnt(1)
	v_mfma_f32_32x32x16_bf16 v[66:81], v[166:169], v[98:101], v[66:81]
	v_add_u32_e32 v171, s66, v184
	v_add_u32_e32 v171, v171, v189
	v_add_u32_e32 v204, 0x6000, v171
	v_add_u32_e32 v205, 0x7000, v171
	v_add_u32_e32 v206, 0x8000, v171
	v_add_u32_e32 v207, 0x9000, v171
	ds_read2_b64 v[166:169], v204 offset0:128 offset1:130
	s_nop 4
	v_max_f32_e32 v172, v67, v67
	v_max_f32_e32 v173, v66, v66
	v_max_f32_e32 v172, v173, v172
	s_waitcnt lgkmcnt(1)
	v_mfma_f32_32x32x16_bf16 v[82:97], v[212:215], v[98:101], v[82:97]
	v_max3_f32 v172, v172, v68, v69
	v_max3_f32 v172, v172, v70, v71
	v_max3_f32 v172, v172, v72, v73
	v_max3_f32 v172, v172, v74, v75
	v_max3_f32 v172, v172, v76, v77
	v_max3_f32 v172, v172, v78, v79
	v_max3_f32 v172, v172, v80, v81
	s_nop 4
	v_max3_f32 v172, v172, v82, v83
	v_max3_f32 v172, v172, v84, v85
	v_max3_f32 v172, v172, v86, v87
	v_max3_f32 v172, v172, v88, v89
	v_max3_f32 v172, v172, v90, v91
	v_max3_f32 v172, v172, v92, v93
	v_max3_f32 v172, v172, v94, v95
	v_max3_f32 v172, v172, v96, v97
	ds_bpermute_b32 v173, v185, v172
	ds_read2_b64 v[178:181], v205 offset0:160 offset1:162
	ds_read2_b64 v[174:177], v206 offset0:192 offset1:194
	s_waitcnt lgkmcnt(2)
	v_max_f32_e32 v237, v172, v173
	v_cmp_lt_f32_e32 vcc, 0x41000000, v237
	ds_read2_b64 v[170:173], v207 offset0:224 offset1:226
	s_cmp_eq_u32 s64, 0
	s_cbranch_scc1 .Lfold_0_upd
	s_cbranch_vccz .Lfold_0_keep
.Lfold_0_upd:
	s_cmp_eq_u32 s64, 0
	s_cbranch_scc1 .Lfold_0_first
	v_max_f32_e32 v237, 0, v237
	v_exp_f32_e64 v196, -v237
	s_branch .Lfold_0_go
.Lfold_0_first:
	v_mov_b32_e32 v196, 0
; DI void attn_unit(LAS unsigned char* lds, int wid, int b, int h, int qb) {
;     ...
;             if (__builtin_amdgcn_ballot_w64(alpha != 1.f) != 0ull) {
; #pragma unroll
;                 for (int dt = 0; dt < 4; ++dt)
; #pragma unroll
;                     for (int i = 0; i < 16; ++i) o[dt][i] *= alpha;
;             }
.Lfold_0_go:
	s_nop 0
	v_pk_mul_f32 v[64:65], v[64:65], v[196:197] op_sel_hi:[1,0]
	v_pk_mul_f32 v[62:63], v[62:63], v[196:197] op_sel_hi:[1,0]
	v_pk_mul_f32 v[60:61], v[60:61], v[196:197] op_sel_hi:[1,0]
	v_pk_mul_f32 v[58:59], v[58:59], v[196:197] op_sel_hi:[1,0]
	v_pk_mul_f32 v[56:57], v[56:57], v[196:197] op_sel_hi:[1,0]
	v_pk_mul_f32 v[54:55], v[54:55], v[196:197] op_sel_hi:[1,0]
	v_pk_mul_f32 v[52:53], v[52:53], v[196:197] op_sel_hi:[1,0]
	v_pk_mul_f32 v[50:51], v[50:51], v[196:197] op_sel_hi:[1,0]
	v_pk_mul_f32 v[48:49], v[48:49], v[196:197] op_sel_hi:[1,0]
	v_pk_mul_f32 v[46:47], v[46:47], v[196:197] op_sel_hi:[1,0]
	v_pk_mul_f32 v[44:45], v[44:45], v[196:197] op_sel_hi:[1,0]
	v_pk_mul_f32 v[42:43], v[42:43], v[196:197] op_sel_hi:[1,0]
	v_pk_mul_f32 v[40:41], v[40:41], v[196:197] op_sel_hi:[1,0]
	v_pk_mul_f32 v[38:39], v[38:39], v[196:197] op_sel_hi:[1,0]
	v_pk_mul_f32 v[36:37], v[36:37], v[196:197] op_sel_hi:[1,0]
	v_pk_mul_f32 v[34:35], v[34:35], v[196:197] op_sel_hi:[1,0]
	v_pk_mul_f32 v[32:33], v[32:33], v[196:197] op_sel_hi:[1,0]
	v_pk_mul_f32 v[30:31], v[30:31], v[196:197] op_sel_hi:[1,0]
	v_pk_mul_f32 v[28:29], v[28:29], v[196:197] op_sel_hi:[1,0]
	v_pk_mul_f32 v[26:27], v[26:27], v[196:197] op_sel_hi:[1,0]
	v_pk_mul_f32 v[24:25], v[24:25], v[196:197] op_sel_hi:[1,0]
	v_pk_mul_f32 v[22:23], v[22:23], v[196:197] op_sel_hi:[1,0]
	v_pk_mul_f32 v[20:21], v[20:21], v[196:197] op_sel_hi:[1,0]
	v_pk_mul_f32 v[18:19], v[18:19], v[196:197] op_sel_hi:[1,0]
	v_pk_mul_f32 v[16:17], v[16:17], v[196:197] op_sel_hi:[1,0]
	v_pk_mul_f32 v[14:15], v[14:15], v[196:197] op_sel_hi:[1,0]
	v_pk_mul_f32 v[12:13], v[12:13], v[196:197] op_sel_hi:[1,0]
	v_pk_mul_f32 v[10:11], v[10:11], v[196:197] op_sel_hi:[1,0]
	v_pk_mul_f32 v[8:9], v[8:9], v[196:197] op_sel_hi:[1,0]
	v_pk_mul_f32 v[6:7], v[6:7], v[196:197] op_sel_hi:[1,0]
	v_pk_mul_f32 v[4:5], v[4:5], v[196:197] op_sel_hi:[1,0]
	v_pk_mul_f32 v[2:3], v[2:3], v[196:197] op_sel_hi:[1,0]
	v_sub_f32_e32 v66, v66, v237
	v_sub_f32_e32 v82, v82, v237
	v_sub_f32_e32 v67, v67, v237
	v_sub_f32_e32 v83, v83, v237
	v_sub_f32_e32 v68, v68, v237
	v_sub_f32_e32 v84, v84, v237
	v_sub_f32_e32 v69, v69, v237
	v_sub_f32_e32 v85, v85, v237
	v_sub_f32_e32 v70, v70, v237
	v_sub_f32_e32 v86, v86, v237
	v_sub_f32_e32 v71, v71, v237
	v_sub_f32_e32 v87, v87, v237
	v_sub_f32_e32 v72, v72, v237
	v_sub_f32_e32 v88, v88, v237
	v_sub_f32_e32 v73, v73, v237
	v_sub_f32_e32 v89, v89, v237
	v_sub_f32_e32 v74, v74, v237
	v_sub_f32_e32 v90, v90, v237
	v_sub_f32_e32 v75, v75, v237
	v_sub_f32_e32 v91, v91, v237
	v_sub_f32_e32 v76, v76, v237
	v_sub_f32_e32 v92, v92, v237
	v_sub_f32_e32 v77, v77, v237
	v_sub_f32_e32 v93, v93, v237
	v_sub_f32_e32 v78, v78, v237
	v_sub_f32_e32 v94, v94, v237
	v_sub_f32_e32 v79, v79, v237
	v_sub_f32_e32 v95, v95, v237
	v_sub_f32_e32 v80, v80, v237
	v_sub_f32_e32 v96, v96, v237
	v_sub_f32_e32 v81, v81, v237
	v_sub_f32_e32 v97, v97, v237
	v_sub_f32_e32 v216, v216, v237
	v_sub_f32_e32 v217, v217, v237
	v_sub_f32_e32 v218, v218, v237
	v_sub_f32_e32 v219, v219, v237
	v_sub_f32_e32 v220, v220, v237
	v_sub_f32_e32 v221, v221, v237
	v_sub_f32_e32 v222, v222, v237
	v_sub_f32_e32 v223, v223, v237
	v_sub_f32_e32 v224, v224, v237
	v_sub_f32_e32 v225, v225, v237
	v_sub_f32_e32 v226, v226, v237
	v_sub_f32_e32 v227, v227, v237
	v_sub_f32_e32 v228, v228, v237
	v_sub_f32_e32 v229, v229, v237
	v_sub_f32_e32 v230, v230, v237
	v_sub_f32_e32 v231, v231, v237
	s_branch .LBB0_1082
.Lfold_0_keep:
	v_mov_b32_e32 v196, 1.0
; DI unsigned pk2(float a, float b) { f32x2 f = {a, b}; bf16v2 r = __builtin_convertvector(f, bf16v2); return __builtin_bit_cast(unsigned, r); }
; #define VLD(dst, j, dt) do { LAS unsigned char* va_ = vb + (32 * (dt) + n) * VROW + (16 * (j) + 4 * g) * 2; const u32x2 lo_ = *(const LAS u32x2*)(va_), hi_ = *(const LAS u32x2*)(va_ + 16); dst = (u32x4){lo_.x, lo_.y, hi_.x, hi_.y}; } while (0)
; DI void attn_unit(LAS unsigned char* lds, int wid, int b, int h, int qb) {
;     ...
;             const float mnew = fmaxf(mrow, mx), alpha = __builtin_amdgcn_exp2f(mrow - mnew); mrow = mnew;
;             float ls = 0.f;
; #pragma unroll
;             for (int i = 0; i < 16; ++i) { s0[i] = __builtin_amdgcn_exp2f(s0[i] - mnew); s1[i] = __builtin_amdgcn_exp2f(s1[i] - mnew); ls += s0[i] + s1[i]; }
;             lrow = lrow * alpha + ls;
;             if (__builtin_amdgcn_ballot_w64(alpha != 1.f) != 0ull) {
; #pragma unroll
;                 for (int dt = 0; dt < 4; ++dt)
; #pragma unroll
;                     for (int i = 0; i < 16; ++i) o[dt][i] *= alpha;
;             }
;             bf16x8 pf[4];
; #pragma unroll
;             for (int jj = 0; jj < 2; ++jj) { u32x4 w0, w1;
;                 w0.x = pk2(s0[8 * jj + 0], s0[8 * jj + 1]); w0.y = pk2(s0[8 * jj + 2], s0[8 * jj + 3]); w0.z = pk2(s0[8 * jj + 4], s0[8 * jj + 5]); w0.w = pk2(s0[8 * jj + 6], s0[8 * jj + 7]);
;                 w1.x = pk2(s1[8 * jj + 0], s1[8 * jj + 1]); w1.y = pk2(s1[8 * jj + 2], s1[8 * jj + 3]); w1.z = pk2(s1[8 * jj + 4], s1[8 * jj + 5]); w1.w = pk2(s1[8 * jj + 6], s1[8 * jj + 7]);
;                 pf[jj] = __builtin_bit_cast(bf16x8, w0); pf[2 + jj] = __builtin_bit_cast(bf16x8, w1); }
; #pragma unroll
;             for (int j = 0; j < 4; ++j) {
;                 if (j < 3) {
; #pragma unroll
;                     for (int dt = 0; dt < 4; ++dt) VLD(vf[(j + 1) & 1][dt], j + 1, dt);
;                 }
; #pragma unroll
;                 for (int dt = 0; dt < 4; ++dt) o[dt] = __builtin_amdgcn_mfma_f32_32x32x16_bf16(__builtin_bit_cast(bf16x8, vf[j & 1][dt]), pf[j], o[dt], 0, 0, 0);
;                 __builtin_amdgcn_sched_barrier(0); }
.LBB0_1082:
	v_exp_f32_e32 v66, v66
	v_exp_f32_e32 v82, v82
	v_exp_f32_e32 v67, v67
	v_exp_f32_e32 v83, v83
	v_exp_f32_e32 v68, v68
	v_exp_f32_e32 v84, v84
	v_exp_f32_e32 v69, v69
	v_exp_f32_e32 v85, v85
	v_add_f32_e32 v208, v82, v66
	v_exp_f32_e32 v70, v70
	v_exp_f32_e32 v86, v86
	v_add_f32_e32 v208, 0, v208
	v_add_f32_e32 v209, v83, v67
	v_exp_f32_e32 v71, v71
	v_exp_f32_e32 v87, v87
	v_add_f32_e32 v208, v209, v208
	v_add_f32_e32 v209, v84, v68
	v_exp_f32_e32 v72, v72
	v_exp_f32_e32 v88, v88
	v_add_f32_e32 v208, v209, v208
	v_add_f32_e32 v209, v85, v69
	v_exp_f32_e32 v73, v73
	v_exp_f32_e32 v89, v89
	v_add_f32_e32 v208, v209, v208
	v_add_f32_e32 v209, v86, v70
	v_exp_f32_e32 v74, v74
	v_exp_f32_e32 v90, v90
	v_add_f32_e32 v208, v209, v208
	v_add_f32_e32 v209, v87, v71
	v_exp_f32_e32 v75, v75
	v_exp_f32_e32 v91, v91
	v_add_f32_e32 v208, v209, v208
	v_add_f32_e32 v209, v88, v72
	v_exp_f32_e32 v76, v76
	v_exp_f32_e32 v92, v92
	v_add_f32_e32 v208, v209, v208
	v_add_f32_e32 v209, v89, v73
	v_exp_f32_e32 v77, v77
	v_exp_f32_e32 v93, v93
	v_add_f32_e32 v208, v209, v208
	v_add_f32_e32 v209, v90, v74
	v_exp_f32_e32 v78, v78
	v_exp_f32_e32 v94, v94
	v_add_f32_e32 v208, v209, v208
	v_add_f32_e32 v209, v91, v75
	v_exp_f32_e32 v79, v79
	v_exp_f32_e32 v95, v95
	v_add_f32_e32 v208, v209, v208
	v_add_f32_e32 v209, v92, v76
	v_exp_f32_e32 v80, v80
	v_exp_f32_e32 v96, v96
	v_add_f32_e32 v208, v209, v208
	v_add_f32_e32 v209, v93, v77
	v_exp_f32_e32 v81, v81
	v_exp_f32_e32 v97, v97
	v_add_f32_e32 v208, v209, v208
	v_add_f32_e32 v209, v94, v78
	v_add_f32_e32 v208, v209, v208
	v_add_f32_e32 v209, v95, v79
	v_add_f32_e32 v208, v209, v208
	v_cvt_pk_bf16_f32 v66, v66, v67
	v_cvt_pk_bf16_f32 v67, v68, v69
	v_cvt_pk_bf16_f32 v68, v70, v71
	v_cvt_pk_bf16_f32 v69, v72, v73
	v_add_f32_e32 v70, v96, v80
	v_add_f32_e32 v70, v70, v208
	v_mfma_f32_32x32x16_bf16 v[50:65], v[166:169], v[66:69], v[50:65]
	v_add_f32_e32 v71, v97, v81
	v_add_f32_e32 v166, v71, v70
	v_cvt_pk_bf16_f32 v70, v82, v83
	v_cvt_pk_bf16_f32 v71, v84, v85
	v_cvt_pk_bf16_f32 v72, v86, v87
	v_cvt_pk_bf16_f32 v73, v88, v89
	v_cvt_pk_bf16_f32 v74, v74, v75
	s_waitcnt lgkmcnt(2)
	v_mfma_f32_32x32x16_bf16 v[34:49], v[178:181], v[66:69], v[34:49]
	v_cvt_pk_bf16_f32 v75, v76, v77
	v_cvt_pk_bf16_f32 v76, v78, v79
	v_cvt_pk_bf16_f32 v77, v80, v81
	v_cvt_pk_bf16_f32 v78, v90, v91
	v_cvt_pk_bf16_f32 v79, v92, v93
	v_cvt_pk_bf16_f32 v80, v94, v95
	v_cvt_pk_bf16_f32 v81, v96, v97
	s_waitcnt lgkmcnt(1)
	v_mfma_f32_32x32x16_bf16 v[18:33], v[174:177], v[66:69], v[18:33]
	ds_read2_b64 v[82:85], v204 offset0:132 offset1:134
	ds_read2_b64 v[86:89], v205 offset0:164 offset1:166
	ds_read2_b64 v[90:93], v206 offset0:196 offset1:198
	ds_read2_b64 v[94:97], v207 offset0:228 offset1:230
	v_fmac_f32_e32 v166, v187, v196
	s_waitcnt lgkmcnt(4)
	v_mfma_f32_32x32x16_bf16 v[2:17], v[170:173], v[66:69], v[2:17]
	s_waitcnt lgkmcnt(3)
	v_mfma_f32_32x32x16_bf16 v[50:65], v[82:85], v[74:77], v[50:65]
	s_waitcnt lgkmcnt(2)
	v_mfma_f32_32x32x16_bf16 v[34:49], v[86:89], v[74:77], v[34:49]
	s_waitcnt lgkmcnt(1)
	v_mfma_f32_32x32x16_bf16 v[18:33], v[90:93], v[74:77], v[18:33]
	ds_read2_b64 v[66:69], v204 offset0:136 offset1:138
	ds_read2_b64 v[82:85], v205 offset0:168 offset1:170
	ds_read2_b64 v[86:89], v206 offset0:200 offset1:202
	ds_read2_b64 v[90:93], v207 offset0:232 offset1:234
	s_waitcnt lgkmcnt(4)
	v_mfma_f32_32x32x16_bf16 v[2:17], v[94:97], v[74:77], v[2:17]
	s_waitcnt lgkmcnt(3)
	v_mfma_f32_32x32x16_bf16 v[50:65], v[66:69], v[70:73], v[50:65]
	s_waitcnt lgkmcnt(2)
	v_mfma_f32_32x32x16_bf16 v[34:49], v[82:85], v[70:73], v[34:49]
	s_waitcnt lgkmcnt(1)
	v_mfma_f32_32x32x16_bf16 v[18:33], v[86:89], v[70:73], v[18:33]
	ds_read2_b64 v[66:69], v204 offset0:140 offset1:142
	ds_read2_b64 v[74:77], v205 offset0:172 offset1:174
	ds_read2_b64 v[82:85], v206 offset0:204 offset1:206
	ds_read2_b64 v[86:89], v207 offset0:236 offset1:238
	s_waitcnt lgkmcnt(4)
	v_mfma_f32_32x32x16_bf16 v[2:17], v[90:93], v[70:73], v[2:17]
	s_waitcnt lgkmcnt(3)
	v_mfma_f32_32x32x16_bf16 v[50:65], v[66:69], v[78:81], v[50:65]
	s_waitcnt lgkmcnt(2)
	v_mfma_f32_32x32x16_bf16 v[34:49], v[74:77], v[78:81], v[34:49]
	s_waitcnt lgkmcnt(1)
	v_mfma_f32_32x32x16_bf16 v[18:33], v[82:85], v[78:81], v[18:33]
	s_waitcnt lgkmcnt(0)
	v_mfma_f32_32x32x16_bf16 v[2:17], v[86:89], v[78:81], v[2:17]
	v_mov_b32_e32 v187, v166
	s_branch .LBB0_1084

; #define LAS __attribute__((address_space(3)))
; DI float shfl_xor_l(float v, int lane, int m) { return __int_as_float(__builtin_amdgcn_ds_bpermute((lane ^ m) << 2, __float_as_int(v))); }
; #define VLD(dst, j, dt) do { LAS unsigned char* va_ = vb + (32 * (dt) + n) * VROW + (16 * (j) + 4 * g) * 2; const u32x2 lo_ = *(const LAS u32x2*)(va_), hi_ = *(const LAS u32x2*)(va_ + 16); dst = (u32x4){lo_.x, lo_.y, hi_.x, hi_.y}; } while (0)
; DI void attn_unit(LAS unsigned char* lds, int wid, int b, int h, int qb) {
;     ...
;         if (kt <= cq) {
;             LAS unsigned char* kb = lds + buf * ABUF; LAS unsigned char* vb = kb + KBYTES;
;             f32x16 s0, s1;
; #pragma unroll
;             for (int i = 0; i < 16; ++i) { s0[i] = 0.f; s1[i] = 0.f; }
;     ...
;             bf16x8 ka[3][2];
;             ka[0][0] = KLD(0, 0); ka[0][1] = KLD(0, 1); ka[1][0] = KLD(1, 0); ka[1][1] = KLD(1, 1);
; #pragma unroll
;             for (int ks = 0; ks < 12; ++ks) {
;                 if (ks + 2 < 12) { ka[(ks + 2) % 3][0] = KLD(ks + 2, 0); ka[(ks + 2) % 3][1] = KLD(ks + 2, 1); }
;                 s0 = __builtin_amdgcn_mfma_f32_32x32x16_bf16(ka[ks % 3][0], qf[ks], s0, 0, 0, 0); s1 = __builtin_amdgcn_mfma_f32_32x32x16_bf16(ka[ks % 3][1], qf[ks], s1, 0, 0, 0);
;                 __builtin_amdgcn_sched_barrier(0); }
;             u32x4 vf[2][4];
; #pragma unroll
;             for (int dt = 0; dt < 4; ++dt) VLD(vf[0][dt], 0, dt);
;             float mx = s0[0];
; #pragma unroll
;             for (int i = 1; i < 16; ++i) mx = fmaxf(mx, s0[i]);
; #pragma unroll
;             for (int i = 0; i < 16; ++i) mx = fmaxf(mx, s1[i]);
;             mx = fmaxf(mx, shfl_xor_l(mx, lane, 32));
;             const float mnew = fmaxf(mrow, mx), alpha = __builtin_amdgcn_exp2f(mrow - mnew); mrow = mnew;
;             float ls = 0.f;
; #pragma unroll
;             for (int i = 0; i < 16; ++i) { s0[i] = __builtin_amdgcn_exp2f(s0[i] - mnew); s1[i] = __builtin_amdgcn_exp2f(s1[i] - mnew); ls += s0[i] + s1[i]; }
;             lrow = lrow * alpha + ls;
;             if (__builtin_amdgcn_ballot_w64(alpha != 1.f) != 0ull) {
.LBB0_1086:
	s_or_b32 s61, s61, 2
	s_cmp_ge_u32 s61, s62
	s_cbranch_scc1 .LBB0_1090
	s_bitcmp1_b32 s63, 0
	s_cselect_b32 s61, 0xa800, 0
	s_add_i32 s61, s61, 0
	v_add3_u32 v162, s61, v199, v202
	ds_read_b128 v[66:69], v162
	ds_read_b128 v[146:149], v162 offset:32
	ds_read_b128 v[82:85], v162 offset:12800
	ds_read_b128 v[150:153], v162 offset:64
	ds_read_b128 v[154:157], v162 offset:12832
	ds_read_b128 v[158:161], v162 offset:12864
	s_waitcnt lgkmcnt(3)
	v_mfma_f32_32x32x16_bf16 v[82:97], v[82:85], v[142:145], v[216:231]
	v_mfma_f32_32x32x16_bf16 v[66:81], v[66:69], v[142:145], v[216:231]
	v_mfma_f32_32x32x16_bf16 v[66:81], v[146:149], v[138:141], v[66:81]
	ds_read_b128 v[142:145], v162 offset:96
	ds_read_b128 v[146:149], v162 offset:12896
	s_waitcnt lgkmcnt(3)
	v_mfma_f32_32x32x16_bf16 v[82:97], v[154:157], v[138:141], v[82:97]
	v_mfma_f32_32x32x16_bf16 v[66:81], v[150:153], v[134:137], v[66:81]
	ds_read_b128 v[138:141], v162 offset:128
	ds_read_b128 v[150:153], v162 offset:12928
	s_waitcnt lgkmcnt(4)
	v_mfma_f32_32x32x16_bf16 v[82:97], v[158:161], v[134:137], v[82:97]
	s_waitcnt lgkmcnt(3)
	v_mfma_f32_32x32x16_bf16 v[66:81], v[142:145], v[130:133], v[66:81]
	ds_read_b128 v[134:137], v162 offset:160
	ds_read_b128 v[142:145], v162 offset:12960
	s_waitcnt lgkmcnt(4)
	v_mfma_f32_32x32x16_bf16 v[82:97], v[146:149], v[130:133], v[82:97]
	s_waitcnt lgkmcnt(3)
	v_mfma_f32_32x32x16_bf16 v[66:81], v[138:141], v[126:129], v[66:81]
	ds_read_b128 v[130:133], v162 offset:192
	ds_read_b128 v[138:141], v162 offset:12992
	s_waitcnt lgkmcnt(4)
	v_mfma_f32_32x32x16_bf16 v[82:97], v[150:153], v[126:129], v[82:97]
	s_waitcnt lgkmcnt(3)
	v_mfma_f32_32x32x16_bf16 v[66:81], v[134:137], v[122:125], v[66:81]
	ds_read_b128 v[126:129], v162 offset:224
	ds_read_b128 v[134:137], v162 offset:13024
	s_waitcnt lgkmcnt(4)
	v_mfma_f32_32x32x16_bf16 v[82:97], v[142:145], v[122:125], v[82:97]
	s_waitcnt lgkmcnt(3)
	v_mfma_f32_32x32x16_bf16 v[66:81], v[130:133], v[118:121], v[66:81]
	ds_read_b128 v[122:125], v162 offset:256
	ds_read_b128 v[130:133], v162 offset:13056
	s_waitcnt lgkmcnt(4)
	v_mfma_f32_32x32x16_bf16 v[82:97], v[138:141], v[118:121], v[82:97]
	s_waitcnt lgkmcnt(3)
	v_mfma_f32_32x32x16_bf16 v[66:81], v[126:129], v[114:117], v[66:81]
	ds_read_b128 v[118:121], v162 offset:288
	ds_read_b128 v[126:129], v162 offset:13088
	s_waitcnt lgkmcnt(4)
	v_mfma_f32_32x32x16_bf16 v[82:97], v[134:137], v[114:117], v[82:97]
	s_waitcnt lgkmcnt(3)
	v_mfma_f32_32x32x16_bf16 v[66:81], v[122:125], v[110:113], v[66:81]
	ds_read_b128 v[114:117], v162 offset:320
	ds_read_b128 v[122:125], v162 offset:13120
	s_waitcnt lgkmcnt(4)
	v_mfma_f32_32x32x16_bf16 v[82:97], v[130:133], v[110:113], v[82:97]
	s_waitcnt lgkmcnt(3)
	v_mfma_f32_32x32x16_bf16 v[66:81], v[118:121], v[106:109], v[66:81]
	ds_read_b128 v[110:113], v162 offset:352
	ds_read_b128 v[118:121], v162 offset:13152
	s_waitcnt lgkmcnt(4)
	v_mfma_f32_32x32x16_bf16 v[82:97], v[126:129], v[106:109], v[82:97]
	s_waitcnt lgkmcnt(3)
	v_mfma_f32_32x32x16_bf16 v[66:81], v[114:117], v[102:105], v[66:81]
	s_waitcnt lgkmcnt(2)
	v_mfma_f32_32x32x16_bf16 v[82:97], v[122:125], v[102:105], v[82:97]
	s_waitcnt lgkmcnt(1)
	v_mfma_f32_32x32x16_bf16 v[66:81], v[110:113], v[98:101], v[66:81]
	v_add_u32_e32 v102, s61, v184
	v_add_u32_e32 v122, v102, v189
	v_add_u32_e32 v115, 0x6000, v122
	v_add_u32_e32 v116, 0x7000, v122
	v_add_u32_e32 v117, 0x8000, v122
	ds_read2_b64 v[102:105], v115 offset0:128 offset1:130
	ds_read2_b64 v[110:113], v116 offset0:160 offset1:162
	s_nop 4
	v_max_f32_e32 v106, v67, v67
	v_max_f32_e32 v107, v66, v66
	v_max_f32_e32 v106, v107, v106
	s_waitcnt lgkmcnt(2)
	v_mfma_f32_32x32x16_bf16 v[82:97], v[118:121], v[98:101], v[82:97]
	v_max3_f32 v106, v106, v68, v69
	v_max3_f32 v106, v106, v70, v71
	v_max3_f32 v106, v106, v72, v73
	v_max3_f32 v106, v106, v74, v75
	v_max3_f32 v106, v106, v76, v77
	v_max3_f32 v106, v106, v78, v79
	v_max3_f32 v106, v106, v80, v81
	s_nop 4
	v_max3_f32 v98, v106, v82, v83
	v_max3_f32 v98, v98, v84, v85
	v_max3_f32 v98, v98, v86, v87
	v_max3_f32 v98, v98, v88, v89
	v_max3_f32 v98, v98, v90, v91
	v_max3_f32 v98, v98, v92, v93
	v_max3_f32 v98, v98, v94, v95
	v_max3_f32 v98, v98, v96, v97
	ds_bpermute_b32 v99, v185, v98
	v_add_u32_e32 v118, 0x9000, v122
	ds_read2_b64 v[106:109], v117 offset0:192 offset1:194
	s_waitcnt lgkmcnt(1)
	v_max_f32_e32 v237, v98, v99
	v_cmp_lt_f32_e32 vcc, 0x41000000, v237
	ds_read2_b64 v[98:101], v118 offset0:224 offset1:226
	s_cbranch_vccz .Lfold_1_keep
; DI void attn_unit(LAS unsigned char* lds, int wid, int b, int h, int qb) {
;     ...
;             const float mnew = fmaxf(mrow, mx), alpha = __builtin_amdgcn_exp2f(mrow - mnew); mrow = mnew;
;             float ls = 0.f;
; #pragma unroll
;             for (int i = 0; i < 16; ++i) { s0[i] = __builtin_amdgcn_exp2f(s0[i] - mnew); s1[i] = __builtin_amdgcn_exp2f(s1[i] - mnew); ls += s0[i] + s1[i]; }
;             lrow = lrow * alpha + ls;
;             if (__builtin_amdgcn_ballot_w64(alpha != 1.f) != 0ull) {
; #pragma unroll
;                 for (int dt = 0; dt < 4; ++dt)
; #pragma unroll
;                     for (int i = 0; i < 16; ++i) o[dt][i] *= alpha;
;             }
.Lfold_1_upd:
	v_max_f32_e32 v237, 0, v237
	v_exp_f32_e64 v114, -v237
	s_nop 0
	v_pk_mul_f32 v[64:65], v[64:65], v[114:115] op_sel_hi:[1,0]
	v_pk_mul_f32 v[62:63], v[62:63], v[114:115] op_sel_hi:[1,0]
	v_pk_mul_f32 v[60:61], v[60:61], v[114:115] op_sel_hi:[1,0]
	v_pk_mul_f32 v[58:59], v[58:59], v[114:115] op_sel_hi:[1,0]
	v_pk_mul_f32 v[56:57], v[56:57], v[114:115] op_sel_hi:[1,0]
	v_pk_mul_f32 v[54:55], v[54:55], v[114:115] op_sel_hi:[1,0]
	v_pk_mul_f32 v[52:53], v[52:53], v[114:115] op_sel_hi:[1,0]
	v_pk_mul_f32 v[50:51], v[50:51], v[114:115] op_sel_hi:[1,0]
	v_pk_mul_f32 v[48:49], v[48:49], v[114:115] op_sel_hi:[1,0]
	v_pk_mul_f32 v[46:47], v[46:47], v[114:115] op_sel_hi:[1,0]
	v_pk_mul_f32 v[44:45], v[44:45], v[114:115] op_sel_hi:[1,0]
	v_pk_mul_f32 v[42:43], v[42:43], v[114:115] op_sel_hi:[1,0]
	v_pk_mul_f32 v[40:41], v[40:41], v[114:115] op_sel_hi:[1,0]
	v_pk_mul_f32 v[38:39], v[38:39], v[114:115] op_sel_hi:[1,0]
	v_pk_mul_f32 v[36:37], v[36:37], v[114:115] op_sel_hi:[1,0]
	v_pk_mul_f32 v[34:35], v[34:35], v[114:115] op_sel_hi:[1,0]
	v_pk_mul_f32 v[32:33], v[32:33], v[114:115] op_sel_hi:[1,0]
	v_pk_mul_f32 v[30:31], v[30:31], v[114:115] op_sel_hi:[1,0]
	v_pk_mul_f32 v[28:29], v[28:29], v[114:115] op_sel_hi:[1,0]
	v_pk_mul_f32 v[26:27], v[26:27], v[114:115] op_sel_hi:[1,0]
	v_pk_mul_f32 v[24:25], v[24:25], v[114:115] op_sel_hi:[1,0]
	v_pk_mul_f32 v[22:23], v[22:23], v[114:115] op_sel_hi:[1,0]
	v_pk_mul_f32 v[20:21], v[20:21], v[114:115] op_sel_hi:[1,0]
	v_pk_mul_f32 v[18:19], v[18:19], v[114:115] op_sel_hi:[1,0]
	v_pk_mul_f32 v[16:17], v[16:17], v[114:115] op_sel_hi:[1,0]
	v_pk_mul_f32 v[14:15], v[14:15], v[114:115] op_sel_hi:[1,0]
	v_pk_mul_f32 v[12:13], v[12:13], v[114:115] op_sel_hi:[1,0]
	v_pk_mul_f32 v[10:11], v[10:11], v[114:115] op_sel_hi:[1,0]
	v_pk_mul_f32 v[8:9], v[8:9], v[114:115] op_sel_hi:[1,0]
	v_pk_mul_f32 v[6:7], v[6:7], v[114:115] op_sel_hi:[1,0]
	v_pk_mul_f32 v[4:5], v[4:5], v[114:115] op_sel_hi:[1,0]
	v_pk_mul_f32 v[2:3], v[2:3], v[114:115] op_sel_hi:[1,0]
	v_sub_f32_e32 v66, v66, v237
	v_sub_f32_e32 v82, v82, v237
	v_sub_f32_e32 v67, v67, v237
	v_sub_f32_e32 v83, v83, v237
	v_sub_f32_e32 v68, v68, v237
	v_sub_f32_e32 v84, v84, v237
	v_sub_f32_e32 v69, v69, v237
	v_sub_f32_e32 v85, v85, v237
	v_sub_f32_e32 v70, v70, v237
	v_sub_f32_e32 v86, v86, v237
	v_sub_f32_e32 v71, v71, v237
	v_sub_f32_e32 v87, v87, v237
	v_sub_f32_e32 v72, v72, v237
	v_sub_f32_e32 v88, v88, v237
	v_sub_f32_e32 v73, v73, v237
	v_sub_f32_e32 v89, v89, v237
	v_sub_f32_e32 v74, v74, v237
	v_sub_f32_e32 v90, v90, v237
	v_sub_f32_e32 v75, v75, v237
	v_sub_f32_e32 v91, v91, v237
	v_sub_f32_e32 v76, v76, v237
	v_sub_f32_e32 v92, v92, v237
	v_sub_f32_e32 v77, v77, v237
	v_sub_f32_e32 v93, v93, v237
	v_sub_f32_e32 v78, v78, v237
	v_sub_f32_e32 v94, v94, v237
	v_sub_f32_e32 v79, v79, v237
	v_sub_f32_e32 v95, v95, v237
	v_sub_f32_e32 v80, v80, v237
	v_sub_f32_e32 v96, v96, v237
	v_sub_f32_e32 v81, v81, v237
	v_sub_f32_e32 v97, v97, v237
	v_sub_f32_e32 v216, v216, v237
	v_sub_f32_e32 v217, v217, v237
	v_sub_f32_e32 v218, v218, v237
	v_sub_f32_e32 v219, v219, v237
	v_sub_f32_e32 v220, v220, v237
	v_sub_f32_e32 v221, v221, v237
	v_sub_f32_e32 v222, v222, v237
	v_sub_f32_e32 v223, v223, v237
	v_sub_f32_e32 v224, v224, v237
	v_sub_f32_e32 v225, v225, v237
	v_sub_f32_e32 v226, v226, v237
	v_sub_f32_e32 v227, v227, v237
	v_sub_f32_e32 v228, v228, v237
	v_sub_f32_e32 v229, v229, v237
	v_sub_f32_e32 v230, v230, v237
	v_sub_f32_e32 v231, v231, v237
	s_branch .LBB0_1089
.Lfold_1_keep:
	v_mov_b32_e32 v114, 1.0
.LBB0_1089:
	v_exp_f32_e32 v66, v66
	v_exp_f32_e32 v82, v82
	v_exp_f32_e32 v67, v67
	v_exp_f32_e32 v83, v83
	v_exp_f32_e32 v68, v68
	v_exp_f32_e32 v84, v84
	v_exp_f32_e32 v69, v69
	v_exp_f32_e32 v85, v85
	v_add_f32_e32 v120, v82, v66
	v_exp_f32_e32 v70, v70
	v_exp_f32_e32 v86, v86
	v_add_f32_e32 v120, 0, v120
	v_add_f32_e32 v121, v83, v67
	v_exp_f32_e32 v71, v71
	v_exp_f32_e32 v87, v87
	v_add_f32_e32 v120, v121, v120
	v_add_f32_e32 v121, v84, v68
	v_exp_f32_e32 v72, v72
	v_exp_f32_e32 v88, v88
	v_add_f32_e32 v120, v121, v120
	v_add_f32_e32 v121, v85, v69
	v_exp_f32_e32 v73, v73
	v_exp_f32_e32 v89, v89
	v_add_f32_e32 v120, v121, v120
	v_add_f32_e32 v121, v86, v70
	v_exp_f32_e32 v74, v74
	v_exp_f32_e32 v90, v90
	v_add_f32_e32 v120, v121, v120
	v_add_f32_e32 v121, v87, v71
	v_exp_f32_e32 v75, v75
	v_exp_f32_e32 v91, v91
	v_add_f32_e32 v120, v121, v120
	v_add_f32_e32 v121, v88, v72
	v_exp_f32_e32 v76, v76
	v_exp_f32_e32 v92, v92
	v_add_f32_e32 v120, v121, v120
	v_add_f32_e32 v121, v89, v73
	v_exp_f32_e32 v77, v77
	v_exp_f32_e32 v93, v93
	v_add_f32_e32 v120, v121, v120
	v_add_f32_e32 v121, v90, v74
	v_exp_f32_e32 v78, v78
	v_exp_f32_e32 v94, v94
	v_add_f32_e32 v120, v121, v120
	v_add_f32_e32 v121, v91, v75
	v_exp_f32_e32 v79, v79
	v_exp_f32_e32 v95, v95
	v_add_f32_e32 v120, v121, v120
	v_add_f32_e32 v121, v92, v76
	v_exp_f32_e32 v80, v80
	v_exp_f32_e32 v96, v96
	v_add_f32_e32 v120, v121, v120
	v_add_f32_e32 v121, v93, v77
	v_exp_f32_e32 v81, v81
	v_exp_f32_e32 v97, v97
	v_add_f32_e32 v120, v121, v120
	v_add_f32_e32 v121, v94, v78
	v_add_f32_e32 v120, v121, v120
	v_add_f32_e32 v121, v95, v79
	v_add_f32_e32 v120, v121, v120
	v_cvt_pk_bf16_f32 v66, v66, v67
	v_cvt_pk_bf16_f32 v67, v68, v69
	v_cvt_pk_bf16_f32 v68, v70, v71
	v_cvt_pk_bf16_f32 v69, v72, v73
	v_add_f32_e32 v70, v96, v80
	v_add_f32_e32 v70, v70, v120
	v_mfma_f32_32x32x16_bf16 v[50:65], v[102:105], v[66:69], v[50:65]
	v_add_f32_e32 v71, v97, v81
	v_add_f32_e32 v102, v71, v70
	v_cvt_pk_bf16_f32 v70, v82, v83
	v_cvt_pk_bf16_f32 v71, v84, v85
	v_cvt_pk_bf16_f32 v72, v86, v87
	v_cvt_pk_bf16_f32 v73, v88, v89
	v_cvt_pk_bf16_f32 v74, v74, v75
	v_mfma_f32_32x32x16_bf16 v[34:49], v[110:113], v[66:69], v[34:49]
	v_cvt_pk_bf16_f32 v75, v76, v77
	v_cvt_pk_bf16_f32 v76, v78, v79
	v_cvt_pk_bf16_f32 v77, v80, v81
	v_cvt_pk_bf16_f32 v78, v90, v91
	v_cvt_pk_bf16_f32 v79, v92, v93
	v_cvt_pk_bf16_f32 v80, v94, v95
	v_cvt_pk_bf16_f32 v81, v96, v97
	s_waitcnt lgkmcnt(1)
; #define LAS __attribute__((address_space(3)))
; DI u32x2 pk4(f32x4 v) { u32x2 r; r.x = pk2(v[0], v[1]); r.y = pk2(v[2], v[3]); return r; }
; DI float shfl_xor_l(float v, int lane, int m) { return __int_as_float(__builtin_amdgcn_ds_bpermute((lane ^ m) << 2, __float_as_int(v))); }
; #define VLD(dst, j, dt) do { LAS unsigned char* va_ = vb + (32 * (dt) + n) * VROW + (16 * (j) + 4 * g) * 2; const u32x2 lo_ = *(const LAS u32x2*)(va_), hi_ = *(const LAS u32x2*)(va_ + 16); dst = (u32x4){lo_.x, lo_.y, hi_.x, hi_.y}; } while (0)
; DI void attn_unit(LAS unsigned char* lds, int wid, int b, int h, int qb) {
;     ...
;             for (int j = 0; j < 4; ++j) {
;                 if (j < 3) {
; #pragma unroll
;                     for (int dt = 0; dt < 4; ++dt) VLD(vf[(j + 1) & 1][dt], j + 1, dt);
;                 }
; #pragma unroll
;                 for (int dt = 0; dt < 4; ++dt) o[dt] = __builtin_amdgcn_mfma_f32_32x32x16_bf16(__builtin_bit_cast(bf16x8, vf[j & 1][dt]), pf[j], o[dt], 0, 0, 0);
;                 __builtin_amdgcn_sched_barrier(0); }
;     ...
;         }
;         if (kt + 1 < nkt) A_WRITE(buf ^ 1);
;         __syncthreads();
;     }
;     ...
;     const float lt = lrow + shfl_xor_l(lrow, lane, 32), inv = 1.f / lt;
;     LAS unsigned char* pt_ = lds + ABUF + wid * (32 * 272);
; #pragma unroll
;     for (int dt = 0; dt < 4; ++dt)
; #pragma unroll
;         for (int blk = 0; blk < 4; ++blk) { const f32x4 v = {o[dt][4 * blk] * inv, o[dt][4 * blk + 1] * inv, o[dt][4 * blk + 2] * inv, o[dt][4 * blk + 3] * inv};
;             *(LAS u32x2*)(pt_ + n * 272 + (32 * dt + 8 * blk + 4 * g) * 2) = pk4(v); }
;     asm volatile("" ::: "memory");
;     bf16_t* od = WSB(OFF_O) + ((size_t)b * SEQ + q0 + (lane >> 4)) * 2048 + h * 128 + (lane & 15) * 8;
; #pragma unroll
;     for (int j = 0; j < 8; ++j) { const u32x4 w = *(const LAS u32x4*)(pt_ + (4 * j + (lane >> 4)) * 272 + (lane & 15) * 16); *(u32x4*)(od + (size_t)(4 * j) * 2048) = w; }
	v_mfma_f32_32x32x16_bf16 v[18:33], v[106:109], v[66:69], v[18:33]
	ds_read2_b64 v[82:85], v115 offset0:132 offset1:134
	ds_read2_b64 v[86:89], v116 offset0:164 offset1:166
	ds_read2_b64 v[90:93], v117 offset0:196 offset1:198
	ds_read2_b64 v[94:97], v118 offset0:228 offset1:230
	v_fmac_f32_e32 v102, v187, v114
	s_waitcnt lgkmcnt(4)
	v_mfma_f32_32x32x16_bf16 v[2:17], v[98:101], v[66:69], v[2:17]
	s_waitcnt lgkmcnt(3)
	v_mfma_f32_32x32x16_bf16 v[50:65], v[82:85], v[74:77], v[50:65]
	s_waitcnt lgkmcnt(2)
	v_mfma_f32_32x32x16_bf16 v[34:49], v[86:89], v[74:77], v[34:49]
	s_waitcnt lgkmcnt(1)
	v_mfma_f32_32x32x16_bf16 v[18:33], v[90:93], v[74:77], v[18:33]
	ds_read2_b64 v[66:69], v115 offset0:136 offset1:138
	ds_read2_b64 v[82:85], v116 offset0:168 offset1:170
	ds_read2_b64 v[86:89], v117 offset0:200 offset1:202
	ds_read2_b64 v[90:93], v118 offset0:232 offset1:234
	s_waitcnt lgkmcnt(4)
	v_mfma_f32_32x32x16_bf16 v[2:17], v[94:97], v[74:77], v[2:17]
	s_waitcnt lgkmcnt(3)
	v_mfma_f32_32x32x16_bf16 v[50:65], v[66:69], v[70:73], v[50:65]
	s_waitcnt lgkmcnt(2)
	v_mfma_f32_32x32x16_bf16 v[34:49], v[82:85], v[70:73], v[34:49]
	s_waitcnt lgkmcnt(1)
	v_mfma_f32_32x32x16_bf16 v[18:33], v[86:89], v[70:73], v[18:33]
	ds_read2_b64 v[66:69], v115 offset0:140 offset1:142
	ds_read2_b64 v[74:77], v116 offset0:172 offset1:174
	ds_read2_b64 v[82:85], v117 offset0:204 offset1:206
	ds_read2_b64 v[86:89], v118 offset0:236 offset1:238
	s_waitcnt lgkmcnt(4)
	v_mfma_f32_32x32x16_bf16 v[2:17], v[90:93], v[70:73], v[2:17]
	s_waitcnt lgkmcnt(3)
	v_mfma_f32_32x32x16_bf16 v[50:65], v[66:69], v[78:81], v[50:65]
	s_waitcnt lgkmcnt(2)
	v_mfma_f32_32x32x16_bf16 v[34:49], v[74:77], v[78:81], v[34:49]
	s_waitcnt lgkmcnt(1)
	v_mfma_f32_32x32x16_bf16 v[18:33], v[82:85], v[78:81], v[18:33]
	s_waitcnt lgkmcnt(0)
	v_mfma_f32_32x32x16_bf16 v[2:17], v[86:89], v[78:81], v[2:17]
	v_mov_b32_e32 v187, v102
.LBB0_1090:
	ds_bpermute_b32 v66, v185, v187
	s_waitcnt lgkmcnt(0)
	s_barrier
	v_mov_b32_e32 v185, v1
	v_add_f32_e32 v66, v187, v66
	v_div_scale_f32 v67, s[62:63], v66, v66, 1.0
	v_rcp_f32_e32 v68, v67
	v_div_scale_f32 v69, vcc, 1.0, v66, 1.0
	v_mov_b32_e32 v187, v201
	v_fma_f32 v70, -v67, v68, 1.0
	v_fmac_f32_e32 v68, v70, v68
	v_mul_f32_e32 v70, v69, v68
	v_fma_f32 v71, -v67, v70, v69
	v_fmac_f32_e32 v70, v71, v68
	v_fma_f32 v67, -v67, v70, v69
	v_div_fmas_f32 v67, v67, v68, v70
	v_div_fixup_f32 v66, v67, v66, 1.0
	v_mul_u32_u24_e32 v67, 0x110, v197
	v_add3_u32 v67, s30, v67, v184
	v_pk_mul_f32 v[2:3], v[2:3], v[66:67] op_sel_hi:[1,0]
	v_pk_mul_f32 v[4:5], v[4:5], v[66:67] op_sel_hi:[1,0]
	v_pk_mul_f32 v[50:51], v[50:51], v[66:67] op_sel_hi:[1,0]
	v_pk_mul_f32 v[52:53], v[52:53], v[66:67] op_sel_hi:[1,0]
	v_cvt_pk_bf16_f32 v2, v2, v3
	v_cvt_pk_bf16_f32 v3, v4, v5
	v_pk_mul_f32 v[4:5], v[6:7], v[66:67] op_sel_hi:[1,0]
	v_pk_mul_f32 v[6:7], v[8:9], v[66:67] op_sel_hi:[1,0]
	v_cvt_pk_bf16_f32 v50, v50, v51
	v_cvt_pk_bf16_f32 v51, v52, v53
	v_pk_mul_f32 v[52:53], v[54:55], v[66:67] op_sel_hi:[1,0]
	v_pk_mul_f32 v[54:55], v[56:57], v[66:67] op_sel_hi:[1,0]
	v_add_u32_e32 v56, 0xa800, v67
	v_cvt_pk_bf16_f32 v4, v4, v5
	v_cvt_pk_bf16_f32 v5, v6, v7
	ds_write2_b64 v56, v[2:3], v[4:5] offset0:24 offset1:26
	v_pk_mul_f32 v[2:3], v[10:11], v[66:67] op_sel_hi:[1,0]
	v_pk_mul_f32 v[4:5], v[12:13], v[66:67] op_sel_hi:[1,0]
	v_pk_mul_f32 v[34:35], v[34:35], v[66:67] op_sel_hi:[1,0]
	v_pk_mul_f32 v[36:37], v[36:37], v[66:67] op_sel_hi:[1,0]
	v_pk_mul_f32 v[18:19], v[18:19], v[66:67] op_sel_hi:[1,0]
	v_pk_mul_f32 v[20:21], v[20:21], v[66:67] op_sel_hi:[1,0]
	v_cvt_pk_bf16_f32 v2, v2, v3
	v_cvt_pk_bf16_f32 v3, v4, v5
	v_pk_mul_f32 v[4:5], v[14:15], v[66:67] op_sel_hi:[1,0]
	v_pk_mul_f32 v[6:7], v[16:17], v[66:67] op_sel_hi:[1,0]
	v_cvt_pk_bf16_f32 v34, v34, v35
	v_cvt_pk_bf16_f32 v35, v36, v37
	v_pk_mul_f32 v[36:37], v[38:39], v[66:67] op_sel_hi:[1,0]
	v_pk_mul_f32 v[38:39], v[40:41], v[66:67] op_sel_hi:[1,0]
	v_cvt_pk_bf16_f32 v18, v18, v19
	v_cvt_pk_bf16_f32 v19, v20, v21
	v_pk_mul_f32 v[20:21], v[22:23], v[66:67] op_sel_hi:[1,0]
	v_pk_mul_f32 v[22:23], v[24:25], v[66:67] op_sel_hi:[1,0]
	v_cvt_pk_bf16_f32 v4, v4, v5
	v_cvt_pk_bf16_f32 v5, v6, v7
	v_cvt_pk_bf16_f32 v52, v52, v53
	v_cvt_pk_bf16_f32 v53, v54, v55
	v_cvt_pk_bf16_f32 v36, v36, v37
	v_cvt_pk_bf16_f32 v37, v38, v39
	v_cvt_pk_bf16_f32 v20, v20, v21
	v_cvt_pk_bf16_f32 v21, v22, v23
	ds_write2_b64 v56, v[2:3], v[4:5] offset0:28 offset1:30
	v_ashrrev_i32_e32 v2, 4, v183
	ds_write2_b64 v56, v[50:51], v[52:53] offset1:2
	v_pk_mul_f32 v[50:51], v[58:59], v[66:67] op_sel_hi:[1,0]
	v_pk_mul_f32 v[52:53], v[60:61], v[66:67] op_sel_hi:[1,0]
	ds_write2_b64 v56, v[34:35], v[36:37] offset0:8 offset1:10
	v_pk_mul_f32 v[34:35], v[42:43], v[66:67] op_sel_hi:[1,0]
	v_pk_mul_f32 v[36:37], v[44:45], v[66:67] op_sel_hi:[1,0]
	ds_write2_b64 v56, v[18:19], v[20:21] offset0:16 offset1:18
	v_pk_mul_f32 v[18:19], v[26:27], v[66:67] op_sel_hi:[1,0]
	v_pk_mul_f32 v[20:21], v[28:29], v[66:67] op_sel_hi:[1,0]
	v_ashrrev_i32_e32 v3, 31, v2
	v_cvt_pk_bf16_f32 v50, v50, v51
	v_cvt_pk_bf16_f32 v51, v52, v53
	v_pk_mul_f32 v[52:53], v[62:63], v[66:67] op_sel_hi:[1,0]
	v_pk_mul_f32 v[54:55], v[64:65], v[66:67] op_sel_hi:[1,0]
	v_cvt_pk_bf16_f32 v34, v34, v35
	v_cvt_pk_bf16_f32 v35, v36, v37
	v_pk_mul_f32 v[36:37], v[46:47], v[66:67] op_sel_hi:[1,0]
	v_pk_mul_f32 v[38:39], v[48:49], v[66:67] op_sel_hi:[1,0]
	v_cvt_pk_bf16_f32 v18, v18, v19
	v_cvt_pk_bf16_f32 v19, v20, v21
	v_pk_mul_f32 v[20:21], v[30:31], v[66:67] op_sel_hi:[1,0]
	v_pk_mul_f32 v[22:23], v[32:33], v[66:67] op_sel_hi:[1,0]
	v_lshl_add_u64 v[4:5], s[26:27], 0, v[2:3]
	v_cvt_pk_bf16_f32 v52, v52, v53
	v_cvt_pk_bf16_f32 v53, v54, v55
	v_cvt_pk_bf16_f32 v36, v36, v37
	v_cvt_pk_bf16_f32 v37, v38, v39
	v_cvt_pk_bf16_f32 v20, v20, v21
	v_cvt_pk_bf16_f32 v21, v22, v23
	v_lshlrev_b64 v[4:5], 12, v[4:5]
	ds_write2_b64 v56, v[50:51], v[52:53] offset0:4 offset1:6
	ds_write2_b64 v56, v[34:35], v[36:37] offset0:12 offset1:14
	ds_write2_b64 v56, v[18:19], v[20:21] offset0:20 offset1:22
	v_lshl_add_u64 v[4:5], s[24:25], 0, v[4:5]
	s_lshl_b32 s24, s4, 1
	s_mov_b32 s25, s5
	v_mul_lo_u32 v2, v2, s46
	v_lshl_add_u64 v[4:5], v[4:5], 0, s[24:25]
	v_lshlrev_b32_e32 v6, 1, v182
	v_mov_b32_e32 v7, v1
	v_add3_u32 v0, s30, v0, v2
	v_lshl_add_u64 v[10:11], v[4:5], 0, v[6:7]
	ds_read_b128 v[2:5], v0 offset:43008
	ds_read_b128 v[6:9], v0 offset:44096
	v_add_co_u32_e32 v12, vcc, s47, v10
	s_mov_b64 s[26:27], s[0:1]
	s_nop 0
	v_addc_co_u32_e32 v13, vcc, 0, v11, vcc
	s_waitcnt lgkmcnt(1)
; #define LAS __attribute__((address_space(3)))
; DI CP* kparams() { CP* kp = (CP*)__builtin_amdgcn_kernarg_segment_ptr(); asm volatile("" : "+s"(kp)); return kp; }
; DI int lane_id() { int l = __builtin_amdgcn_mbcnt_hi(-1, __builtin_amdgcn_mbcnt_lo(-1, 0)); asm volatile("" : "+v"(l)); return l; }
; #define A_LOAD(kt) do { const size_t ko = (size_t)(kt) * 64; st0 = *(const u32x4*)(kn_src + ko * 2048); st1 = *(const u32x4*)(kn_src + (ko + 32) * 2048); \
;         st2 = *(const u32x4*)(kr_src + ko * 64); st3 = *(const u32x4*)(v_src + ko); st4 = *(const u32x4*)(v_src + ko + (size_t)64 * 8192); } while (0)
; DI void attn_unit(LAS unsigned char* lds, int wid, int b, int h, int qb) {
;     CP& p = *kparams();
;     const int lane = lane_id(), tid = wid * 64 + lane, n = lane & 31, g = lane >> 5;
;     const int q0 = qb * 256 + wid * 32, cq = q0 >> 6, nkt = 4 * qb + 4;
;     const size_t tokq = (size_t)b * SEQ + q0 + n;
;     const bf16_t* Q = WSB(OFF_Q); const bf16_t* KN = WSB(OFF_KN); const bf16_t* KR = WSB(OFF_KR); const bf16_t* VT = WSB(OFF_VT2);
;     bf16x8 qf[12];
; #pragma unroll
;     for (int ks = 0; ks < 12; ++ks) qf[ks] = *(const bf16x8*)(Q + tokq * 3072 + h * 192 + ks * 16 + g * 8);
;     f32x16 o[4];
; #pragma unroll
;     for (int dt = 0; dt < 4; ++dt)
; #pragma unroll
;         for (int i = 0; i < 16; ++i) o[dt][i] = 0.f;
;     float mrow = -__builtin_inff(), lrow = 0.f;
;     const int krow = tid >> 4, kc16 = tid & 15, rrow = tid >> 3, rc8 = tid & 7;
;     const bf16_t* kn_src = KN + ((size_t)b * SEQ + krow) * 2048 + h * 128 + kc16 * 8;
;     const bf16_t* kr_src = KR + ((size_t)b * SEQ + rrow) * 64 + rc8 * 8;
;     const bf16_t* v_src = VT + ((size_t)h * 128 + rrow) * 8192 + (size_t)b * SEQ + rc8 * 8;
;     const int kn_dst = krow * KROW + kc16 * 16, kr_dst = rrow * KROW + 256 + rc8 * 16, v_dst = KBYTES + rrow * VROW + rc8 * 16;
;     u32x4 st0, st1, st2, st3, st4;
;     ...
;     A_LOAD(0); A_WRITE(0); __syncthreads();
;     ...
;     bf16_t* od = WSB(OFF_O) + ((size_t)b * SEQ + q0 + (lane >> 4)) * 2048 + h * 128 + (lane & 15) * 8;
; #pragma unroll
;     for (int j = 0; j < 8; ++j) { const u32x4 w = *(const LAS u32x4*)(pt_ + (4 * j + (lane >> 4)) * 272 + (lane & 15) * 16); *(u32x4*)(od + (size_t)(4 * j) * 2048) = w; }
	global_store_dwordx4 v[12:13], v[2:5], off
	v_mov_b32_e32 v172, 0xff800000
	s_nop 0
	v_add_co_u32_e32 v2, vcc, s48, v10
	s_nop 1
	v_addc_co_u32_e32 v3, vcc, 0, v11, vcc
	s_waitcnt lgkmcnt(0)
	global_store_dwordx4 v[2:3], v[6:9], off
	ds_read_b128 v[2:5], v0 offset:45184
	ds_read_b128 v[6:9], v0 offset:46272
	v_add_co_u32_e32 v12, vcc, s49, v10
	s_nop 1
	v_addc_co_u32_e32 v13, vcc, 0, v11, vcc
	s_waitcnt lgkmcnt(1)
	global_store_dwordx4 v[12:13], v[2:5], off
	s_nop 1
	v_add_co_u32_e32 v2, vcc, s50, v10
	s_nop 1
	v_addc_co_u32_e32 v3, vcc, 0, v11, vcc
	s_waitcnt lgkmcnt(0)
	global_store_dwordx4 v[2:3], v[6:9], off
	ds_read_b128 v[2:5], v0 offset:47360
	ds_read_b128 v[6:9], v0 offset:48448
	v_add_co_u32_e32 v12, vcc, s51, v10
	s_nop 1
	v_addc_co_u32_e32 v13, vcc, 0, v11, vcc
	s_waitcnt lgkmcnt(1)
	global_store_dwordx4 v[12:13], v[2:5], off
	s_nop 1
	v_add_co_u32_e32 v2, vcc, s52, v10
	s_nop 1
	v_addc_co_u32_e32 v3, vcc, 0, v11, vcc
	s_waitcnt lgkmcnt(0)
	global_store_dwordx4 v[2:3], v[6:9], off
	ds_read_b128 v[2:5], v0 offset:49536
	ds_read_b128 v[6:9], v0 offset:50624
	v_add_co_u32_e32 v12, vcc, s53, v10
	s_nop 1
	v_addc_co_u32_e32 v13, vcc, 0, v11, vcc
	s_waitcnt lgkmcnt(1)
	global_store_dwordx4 v[12:13], v[2:5], off
	s_nop 1
	v_add_co_u32_e32 v2, vcc, s54, v10
	s_nop 1
	v_addc_co_u32_e32 v3, vcc, 0, v11, vcc
	s_waitcnt lgkmcnt(0)
	global_store_dwordx4 v[2:3], v[6:9], off
	s_load_dwordx2 s[26:27], s[26:27], 0xa8
	v_add_u32_e32 v0, s28, v187
	v_ashrrev_i32_e32 v24, 3, v0
	v_ashrrev_i32_e32 v25, 31, v24
	v_ashrrev_i32_e32 v22, 4, v0
	v_lshl_add_u64 v[4:5], s[16:17], 0, v[24:25]
	v_ashrrev_i32_e32 v23, 31, v22
	v_lshlrev_b64 v[4:5], 7, v[4:5]
	v_lshlrev_b32_e32 v0, 4, v187
	v_lshl_add_u64 v[2:3], s[16:17], 0, v[22:23]
	s_waitcnt lgkmcnt(0)
	v_lshl_add_u64 v[4:5], s[26:27], 0, v[4:5]
	v_and_b32_e32 v0, 0x70, v0
	v_lshlrev_b64 v[2:3], 12, v[2:3]
	v_lshl_add_u64 v[10:11], v[4:5], 0, v[0:1]
	v_lshl_add_u64 v[4:5], v[24:25], 0, s[4:5]
	v_and_b32_e32 v30, 15, v187
	v_lshl_add_u64 v[2:3], s[26:27], 0, v[2:3]
	v_lshlrev_b64 v[4:5], 14, v[4:5]
	v_lshl_add_u64 v[2:3], v[2:3], 0, s[24:25]
	v_lshlrev_b32_e32 v184, 4, v30
	v_lshl_add_u64 v[4:5], s[26:27], 0, v[4:5]
	v_lshl_add_u64 v[2:3], v[2:3], 0, v[184:185]
	v_lshl_add_u64 v[4:5], s[16:17], 1, v[4:5]
	v_lshl_add_u64 v[18:19], v[4:5], 0, v[0:1]
	v_add_co_u32_e32 v4, vcc, s40, v2
	s_and_b32 s4, s57, 7
	s_nop 0
	v_addc_co_u32_e32 v5, vcc, 0, v3, vcc
	v_add_co_u32_e32 v6, vcc, s41, v2
	s_lshl_b32 s4, s4, 2
	s_lshl_b32 s25, s56, 8
	v_addc_co_u32_e32 v7, vcc, 0, v3, vcc
	s_or_b32 s4, s4, 3
	s_add_i32 s25, s25, s29
	v_add_co_u32_e32 v10, vcc, s42, v10
	v_and_b32_e32 v202, 31, v187
	s_add_u32 s16, s16, s25
	v_addc_co_u32_e32 v11, vcc, 0, v11, vcc
	v_or_b32_e32 v28, s16, v202
	v_mov_b64_e32 v[26:27], s[26:27]
	v_add_co_u32_e32 v14, vcc, s43, v18
	v_ashrrev_i32_e32 v31, 5, v187
	s_addc_u32 s17, s17, 0
	v_mad_u64_u32 v[26:27], s[62:63], v28, s37, v[26:27]
	v_addc_co_u32_e32 v15, vcc, 0, v19, vcc
	v_mad_i32_i24 v27, s17, v200, v27
	s_lshl_b32 s62, s58, 1
	s_mov_b32 s63, s5
	v_lshlrev_b32_e32 v188, 3, v31
	v_add_co_u32_e32 v18, vcc, s44, v18
	v_lshl_add_u64 v[26:27], v[26:27], 0, s[62:63]
	v_ashrrev_i32_e32 v189, 31, v188
	global_load_dwordx4 v[2:5], v[4:5], off
	s_nop 0
	global_load_dwordx4 v[6:9], v[6:7], off
	v_addc_co_u32_e32 v19, vcc, 0, v19, vcc
	v_lshl_add_u64 v[26:27], v[188:189], 1, v[26:27]
	global_load_dwordx4 v[10:13], v[10:11], off
	v_lshl_add_u64 v[28:29], v[26:27], 0, s[8:9]
	v_add_co_u32_e32 v26, vcc, s38, v26
	global_load_dwordx4 v[14:17], v[14:15], off
	s_nop 0
	v_addc_co_u32_e32 v27, vcc, 0, v27, vcc
	global_load_dwordx4 v[18:21], v[18:19], off
	s_nop 0
	global_load_dwordx4 v[152:155], v[28:29], off offset:32
	global_load_dwordx4 v[148:151], v[28:29], off offset:64
	global_load_dwordx4 v[144:147], v[28:29], off offset:96
	global_load_dwordx4 v[140:143], v[28:29], off offset:128
	global_load_dwordx4 v[136:139], v[28:29], off offset:160
	global_load_dwordx4 v[132:135], v[28:29], off offset:192
	global_load_dwordx4 v[128:131], v[28:29], off offset:224
	global_load_dwordx4 v[124:127], v[28:29], off offset:256
	global_load_dwordx4 v[120:123], v[28:29], off offset:288
	global_load_dwordx4 v[116:119], v[28:29], off offset:320
	global_load_dwordx4 v[156:159], v[26:27], off
	global_load_dwordx4 v[112:115], v[28:29], off offset:352
	v_mad_u64_u32 v[190:191], s[62:63], v22, s39, v[184:185]
	v_add_u32_e32 v26, 0, v190
	v_mad_u64_u32 v[192:193], s[62:63], v24, s39, v[0:1]
	s_waitcnt vmcnt(16)
	ds_write_b128 v26, v[2:5]
	s_waitcnt vmcnt(15)
	ds_write_b128 v26, v[6:9] offset:12800
	v_add_u32_e32 v2, 0, v192
	v_mul_lo_u32 v3, v24, s45
	s_lshr_b32 s25, s25, 6
	s_waitcnt vmcnt(14)
	ds_write_b128 v2, v[10:13] offset:256
	v_add_u32_e32 v2, v2, v3
	v_add_u32_e32 v203, v192, v3
	v_add_u32_e32 v3, 0x6400, v2
	v_add_u32_e32 v2, 0x8600, v2
	s_add_u32 s18, s18, s59
	s_waitcnt vmcnt(13)
	ds_write2_b64 v3, v[14:15], v[16:17] offset1:1
	s_waitcnt vmcnt(12)
; #define LAS __attribute__((address_space(3)))
; #define A_LOAD(kt) do { const size_t ko = (size_t)(kt) * 64; st0 = *(const u32x4*)(kn_src + ko * 2048); st1 = *(const u32x4*)(kn_src + (ko + 32) * 2048); \
;         st2 = *(const u32x4*)(kr_src + ko * 64); st3 = *(const u32x4*)(v_src + ko); st4 = *(const u32x4*)(v_src + ko + (size_t)64 * 8192); } while (0)
; DI void attn_unit(LAS unsigned char* lds, int wid, int b, int h, int qb) {
;     ...
;     u32x4 st0, st1, st2, st3, st4;
;     ...
;     A_LOAD(0); A_WRITE(0); __syncthreads();
;     for (int kt = 0; kt < nkt; ++kt) {
;         const int buf = kt & 1;
;         if (kt + 1 < nkt) A_LOAD(kt + 1);
;         if (kt <= cq) {
;             LAS unsigned char* kb = lds + buf * ABUF; LAS unsigned char* vb = kb + KBYTES;
;             f32x16 s0, s1;
; #pragma unroll
;             for (int i = 0; i < 16; ++i) { s0[i] = 0.f; s1[i] = 0.f; }
;     ...
;             bf16x8 ka[3][2];
;             ka[0][0] = KLD(0, 0); ka[0][1] = KLD(0, 1); ka[1][0] = KLD(1, 0); ka[1][1] = KLD(1, 1);
; #pragma unroll
;             for (int ks = 0; ks < 12; ++ks) {
;                 if (ks + 2 < 12) { ka[(ks + 2) % 3][0] = KLD(ks + 2, 0); ka[(ks + 2) % 3][1] = KLD(ks + 2, 1); }
;                 s0 = __builtin_amdgcn_mfma_f32_32x32x16_bf16(ka[ks % 3][0], qf[ks], s0, 0, 0, 0); s1 = __builtin_amdgcn_mfma_f32_32x32x16_bf16(ka[ks % 3][1], qf[ks], s1, 0, 0, 0);
	ds_write2_b64 v2, v[18:19], v[20:21] offset1:1
	v_lshlrev_b32_e32 v2, 2, v187
	v_xor_b32_e32 v189, 0x80, v2
	v_lshlrev_b64 v[2:3], 14, v[24:25]
	s_addc_u32 s19, s19, 0
	v_lshl_add_u64 v[2:3], s[18:19], 0, v[2:3]
	v_lshl_add_u64 v[194:195], v[2:3], 0, v[0:1]
	v_lshlrev_b64 v[2:3], 7, v[24:25]
	v_lshl_add_u64 v[2:3], s[20:21], 0, v[2:3]
	s_add_u32 s18, s60, s22
	v_lshl_add_u64 v[196:197], v[2:3], 0, v[0:1]
	v_lshlrev_b64 v[2:3], 12, v[22:23]
	s_addc_u32 s19, 0, s23
	v_lshl_add_u64 v[2:3], s[18:19], 0, v[2:3]
	v_mov_b32_e32 v14, v1
	v_mov_b32_e32 v15, v1
	v_lshlrev_b32_e32 v186, 3, v30
	v_lshlrev_b32_e32 v204, 4, v31
	v_lshl_add_u64 v[198:199], v[2:3], 0, v[184:185]
	v_mov_b32_e32 v0, v1
	v_mov_b32_e32 v2, v1
	v_mov_b32_e32 v3, v1
	v_mov_b32_e32 v4, v1
	v_mov_b32_e32 v5, v1
	v_mov_b32_e32 v6, v1
	v_mov_b32_e32 v7, v1
	v_mov_b32_e32 v8, v1
	v_mov_b32_e32 v9, v1
	v_mov_b32_e32 v10, v1
	v_mov_b32_e32 v11, v1
	v_mov_b32_e32 v12, v1
	v_mov_b32_e32 v13, v1
	v_mov_b64_e32 v[30:31], v[14:15]
	v_mov_b64_e32 v[46:47], v[14:15]
	v_mov_b64_e32 v[62:63], v[14:15]
	v_mov_b64_e32 v[78:79], v[14:15]
	s_mov_b32 s57, 0
	v_mul_u32_u24_e32 v193, 0x190, v202
	v_mul_u32_u24_e32 v191, 0x88, v202
	v_mov_b32_e32 v185, 0
	v_mov_b64_e32 v[28:29], v[12:13]
	v_mov_b64_e32 v[26:27], v[10:11]
	v_mov_b64_e32 v[24:25], v[8:9]
	v_mov_b64_e32 v[22:23], v[6:7]
	v_mov_b64_e32 v[20:21], v[4:5]
	v_mov_b64_e32 v[18:19], v[2:3]
	v_mov_b64_e32 v[16:17], v[0:1]
	v_mov_b64_e32 v[44:45], v[12:13]
	v_mov_b64_e32 v[42:43], v[10:11]
	v_mov_b64_e32 v[40:41], v[8:9]
	v_mov_b64_e32 v[38:39], v[6:7]
	v_mov_b64_e32 v[36:37], v[4:5]
	v_mov_b64_e32 v[34:35], v[2:3]
	v_mov_b64_e32 v[32:33], v[0:1]
	v_mov_b64_e32 v[60:61], v[12:13]
	v_mov_b64_e32 v[58:59], v[10:11]
	v_mov_b64_e32 v[56:57], v[8:9]
	v_mov_b64_e32 v[54:55], v[6:7]
	v_mov_b64_e32 v[52:53], v[4:5]
	v_mov_b64_e32 v[50:51], v[2:3]
	v_mov_b64_e32 v[48:49], v[0:1]
	v_mov_b64_e32 v[76:77], v[12:13]
	v_mov_b64_e32 v[74:75], v[10:11]
	v_mov_b64_e32 v[72:73], v[8:9]
	v_mov_b64_e32 v[70:71], v[6:7]
	v_mov_b64_e32 v[68:69], v[4:5]
	v_mov_b64_e32 v[66:67], v[2:3]
	v_mov_b64_e32 v[64:65], v[0:1]
	s_waitcnt lgkmcnt(0)
	s_barrier
	v_mov_b32_e32 v216, 0
	v_mov_b32_e32 v217, 0
	v_mov_b32_e32 v218, 0
	v_mov_b32_e32 v219, 0
	v_mov_b32_e32 v220, 0
	v_mov_b32_e32 v221, 0
	v_mov_b32_e32 v222, 0
	v_mov_b32_e32 v223, 0
	v_mov_b32_e32 v224, 0
	v_mov_b32_e32 v225, 0
	v_mov_b32_e32 v226, 0
	v_mov_b32_e32 v227, 0
	v_mov_b32_e32 v228, 0
	v_mov_b32_e32 v229, 0
	v_mov_b32_e32 v230, 0
	v_mov_b32_e32 v231, 0
	s_add_u32 s70, s26, 0x11140000
	s_addc_u32 s71, s27, 0
	s_add_u32 s72, s26, 0x11160000
	s_addc_u32 s73, s27, 0
	s_add_u32 s74, s26, 0x13100000
	s_addc_u32 s75, s27, 0
	s_add_u32 s76, s26, 0x13200000
	s_addc_u32 s77, s27, 0
	s_mov_b64 s[78:79], s[26:27]
.LBB0_1091:
	s_and_b32 s18, s57, 1
	global_load_dwordx4 v[2:5], v198, s[70:71]
	global_load_dwordx4 v[6:9], v198, s[72:73]
	global_load_dwordx4 v[10:13], v196, s[78:79]
	global_load_dwordx4 v[160:163], v194, s[74:75] offset:128
	global_load_dwordx4 v[164:167], v194, s[76:77] offset:128
	s_cmp_gt_u32 s57, s25
	s_cbranch_scc1 .LBB0_1095
	s_mul_i32 s19, s18, 0xa800
	s_add_i32 s19, s19, 0
	v_add3_u32 v0, s19, v193, v204
	ds_read_b128 v[80:83], v0
	ds_read_b128 v[168:171], v0 offset:32
	ds_read_b128 v[96:99], v0 offset:12800
	ds_read_b128 v[174:177], v0 offset:64
	ds_read_b128 v[178:181], v0 offset:12832
	ds_read_b128 v[206:209], v0 offset:12864
	s_waitcnt vmcnt(6) lgkmcnt(3)
	v_mfma_f32_32x32x16_bf16 v[96:111], v[96:99], v[156:159], v[216:231]
	v_mfma_f32_32x32x16_bf16 v[80:95], v[80:83], v[156:159], v[216:231]
	v_mfma_f32_32x32x16_bf16 v[80:95], v[168:171], v[152:155], v[80:95]
	ds_read_b128 v[168:171], v0 offset:96
	ds_read_b128 v[210:213], v0 offset:12896
	s_waitcnt lgkmcnt(3)
	v_mfma_f32_32x32x16_bf16 v[96:111], v[178:181], v[152:155], v[96:111]
	v_mfma_f32_32x32x16_bf16 v[80:95], v[174:177], v[148:151], v[80:95]
	ds_read_b128 v[174:177], v0 offset:128
	ds_read_b128 v[178:181], v0 offset:12928
	s_waitcnt lgkmcnt(4)
	v_mfma_f32_32x32x16_bf16 v[96:111], v[206:209], v[148:151], v[96:111]
	s_waitcnt lgkmcnt(3)
	v_mfma_f32_32x32x16_bf16 v[80:95], v[168:171], v[144:147], v[80:95]
	ds_read_b128 v[168:171], v0 offset:160
	ds_read_b128 v[206:209], v0 offset:12960
	s_waitcnt lgkmcnt(4)
	v_mfma_f32_32x32x16_bf16 v[96:111], v[210:213], v[144:147], v[96:111]
	s_waitcnt lgkmcnt(3)
	v_mfma_f32_32x32x16_bf16 v[80:95], v[174:177], v[140:143], v[80:95]
	ds_read_b128 v[174:177], v0 offset:192
	ds_read_b128 v[210:213], v0 offset:12992
	s_waitcnt lgkmcnt(4)
	v_mfma_f32_32x32x16_bf16 v[96:111], v[178:181], v[140:143], v[96:111]
	s_waitcnt lgkmcnt(3)
	v_mfma_f32_32x32x16_bf16 v[80:95], v[168:171], v[136:139], v[80:95]
	ds_read_b128 v[168:171], v0 offset:224
	ds_read_b128 v[178:181], v0 offset:13024
	s_waitcnt lgkmcnt(4)
	v_mfma_f32_32x32x16_bf16 v[96:111], v[206:209], v[136:139], v[96:111]
	s_waitcnt lgkmcnt(3)
	v_mfma_f32_32x32x16_bf16 v[80:95], v[174:177], v[132:135], v[80:95]
	ds_read_b128 v[174:177], v0 offset:256
	ds_read_b128 v[206:209], v0 offset:13056
	s_waitcnt lgkmcnt(4)
	v_mfma_f32_32x32x16_bf16 v[96:111], v[210:213], v[132:135], v[96:111]
	s_waitcnt lgkmcnt(3)
	v_mfma_f32_32x32x16_bf16 v[80:95], v[168:171], v[128:131], v[80:95]
	ds_read_b128 v[168:171], v0 offset:288
	ds_read_b128 v[210:213], v0 offset:13088
	s_waitcnt lgkmcnt(4)
	v_mfma_f32_32x32x16_bf16 v[96:111], v[178:181], v[128:131], v[96:111]
	s_waitcnt lgkmcnt(3)
	v_mfma_f32_32x32x16_bf16 v[80:95], v[174:177], v[124:127], v[80:95]
	ds_read_b128 v[174:177], v0 offset:320
	ds_read_b128 v[178:181], v0 offset:13120
	s_waitcnt lgkmcnt(4)
; DI float shfl_xor_l(float v, int lane, int m) { return __int_as_float(__builtin_amdgcn_ds_bpermute((lane ^ m) << 2, __float_as_int(v))); }
; #define VLD(dst, j, dt) do { LAS unsigned char* va_ = vb + (32 * (dt) + n) * VROW + (16 * (j) + 4 * g) * 2; const u32x2 lo_ = *(const LAS u32x2*)(va_), hi_ = *(const LAS u32x2*)(va_ + 16); dst = (u32x4){lo_.x, lo_.y, hi_.x, hi_.y}; } while (0)
; DI void attn_unit(LAS unsigned char* lds, int wid, int b, int h, int qb) {
;     ...
;                 s0 = __builtin_amdgcn_mfma_f32_32x32x16_bf16(ka[ks % 3][0], qf[ks], s0, 0, 0, 0); s1 = __builtin_amdgcn_mfma_f32_32x32x16_bf16(ka[ks % 3][1], qf[ks], s1, 0, 0, 0);
;                 __builtin_amdgcn_sched_barrier(0); }
;             u32x4 vf[2][4];
; #pragma unroll
;             for (int dt = 0; dt < 4; ++dt) VLD(vf[0][dt], 0, dt);
;             float mx = s0[0];
; #pragma unroll
;             for (int i = 1; i < 16; ++i) mx = fmaxf(mx, s0[i]);
; #pragma unroll
;             for (int i = 0; i < 16; ++i) mx = fmaxf(mx, s1[i]);
;             mx = fmaxf(mx, shfl_xor_l(mx, lane, 32));
;             const float mnew = fmaxf(mrow, mx), alpha = __builtin_amdgcn_exp2f(mrow - mnew); mrow = mnew;
;             float ls = 0.f;
; #pragma unroll
;             for (int i = 0; i < 16; ++i) { s0[i] = __builtin_amdgcn_exp2f(s0[i] - mnew); s1[i] = __builtin_amdgcn_exp2f(s1[i] - mnew); ls += s0[i] + s1[i]; }
;             lrow = lrow * alpha + ls;
;             if (__builtin_amdgcn_ballot_w64(alpha != 1.f) != 0ull) {
; #pragma unroll
;                 for (int dt = 0; dt < 4; ++dt)
; #pragma unroll
;                     for (int i = 0; i < 16; ++i) o[dt][i] *= alpha;
;             }
	v_mfma_f32_32x32x16_bf16 v[96:111], v[206:209], v[124:127], v[96:111]
	s_waitcnt lgkmcnt(3)
	v_mfma_f32_32x32x16_bf16 v[80:95], v[168:171], v[120:123], v[80:95]
	ds_read_b128 v[168:171], v0 offset:352
	ds_read_b128 v[206:209], v0 offset:13152
	s_waitcnt lgkmcnt(4)
	v_mfma_f32_32x32x16_bf16 v[96:111], v[210:213], v[120:123], v[96:111]
	s_waitcnt lgkmcnt(3)
	v_mfma_f32_32x32x16_bf16 v[80:95], v[174:177], v[116:119], v[80:95]
	s_waitcnt lgkmcnt(2)
	v_mfma_f32_32x32x16_bf16 v[96:111], v[178:181], v[116:119], v[96:111]
	s_waitcnt vmcnt(5) lgkmcnt(1)
	v_mfma_f32_32x32x16_bf16 v[80:95], v[168:171], v[112:115], v[80:95]
	v_add_u32_e32 v0, s19, v188
	v_add_u32_e32 v173, v0, v191
	v_add_u32_e32 v15, 0x6000, v173
	v_add_u32_e32 v205, 0x7000, v173
	ds_read2_b64 v[168:171], v15 offset0:128 offset1:130
	ds_read2_b64 v[180:183], v205 offset0:160 offset1:162
	s_nop 5
	v_max_f32_e32 v0, v81, v81
	v_max_f32_e32 v14, v80, v80
	v_max_f32_e32 v0, v14, v0
	s_waitcnt lgkmcnt(2)
	v_mfma_f32_32x32x16_bf16 v[96:111], v[206:209], v[112:115], v[96:111]
	v_max3_f32 v0, v0, v82, v83
	v_max3_f32 v0, v0, v84, v85
	v_max3_f32 v0, v0, v86, v87
	v_max3_f32 v0, v0, v88, v89
	v_max3_f32 v0, v0, v90, v91
	v_max3_f32 v0, v0, v92, v93
	v_max3_f32 v0, v0, v94, v95
	s_nop 4
	v_max3_f32 v0, v0, v96, v97
	v_max3_f32 v0, v0, v98, v99
	v_max3_f32 v0, v0, v100, v101
	v_max3_f32 v0, v0, v102, v103
	v_max3_f32 v0, v0, v104, v105
	v_max3_f32 v0, v0, v106, v107
	v_max3_f32 v0, v0, v108, v109
	v_max3_f32 v0, v0, v110, v111
	ds_bpermute_b32 v14, v189, v0
	v_add_u32_e32 v206, 0x8000, v173
	v_add_u32_e32 v207, 0x9000, v173
	ds_read2_b64 v[176:179], v206 offset0:192 offset1:194
	s_waitcnt lgkmcnt(1)
	v_max_f32_e32 v237, v0, v14
	v_cmp_lt_f32_e32 vcc, 0x41000000, v237
	ds_read2_b64 v[172:175], v207 offset0:224 offset1:226
	s_cmp_eq_u32 s57, 0
	s_cbranch_scc1 .Lfold_2_upd
	s_cbranch_vccz .Lfold_2_keep
.Lfold_2_upd:
	s_cmp_eq_u32 s57, 0
	s_cbranch_scc1 .Lfold_2_first
	v_max_f32_e32 v237, 0, v237
	v_exp_f32_e64 v0, -v237
	s_branch .Lfold_2_go
.Lfold_2_first:
	v_mov_b32_e32 v0, 0
.Lfold_2_go:
	s_nop 0
	v_pk_mul_f32 v[78:79], v[78:79], v[0:1] op_sel_hi:[1,0]
	v_pk_mul_f32 v[76:77], v[76:77], v[0:1] op_sel_hi:[1,0]
	v_pk_mul_f32 v[74:75], v[74:75], v[0:1] op_sel_hi:[1,0]
	v_pk_mul_f32 v[72:73], v[72:73], v[0:1] op_sel_hi:[1,0]
	v_pk_mul_f32 v[70:71], v[70:71], v[0:1] op_sel_hi:[1,0]
	v_pk_mul_f32 v[68:69], v[68:69], v[0:1] op_sel_hi:[1,0]
	v_pk_mul_f32 v[66:67], v[66:67], v[0:1] op_sel_hi:[1,0]
	v_pk_mul_f32 v[64:65], v[64:65], v[0:1] op_sel_hi:[1,0]
	v_pk_mul_f32 v[62:63], v[62:63], v[0:1] op_sel_hi:[1,0]
	v_pk_mul_f32 v[60:61], v[60:61], v[0:1] op_sel_hi:[1,0]
	v_pk_mul_f32 v[58:59], v[58:59], v[0:1] op_sel_hi:[1,0]
	v_pk_mul_f32 v[56:57], v[56:57], v[0:1] op_sel_hi:[1,0]
	v_pk_mul_f32 v[54:55], v[54:55], v[0:1] op_sel_hi:[1,0]
	v_pk_mul_f32 v[52:53], v[52:53], v[0:1] op_sel_hi:[1,0]
	v_pk_mul_f32 v[50:51], v[50:51], v[0:1] op_sel_hi:[1,0]
	v_pk_mul_f32 v[48:49], v[48:49], v[0:1] op_sel_hi:[1,0]
	v_pk_mul_f32 v[46:47], v[46:47], v[0:1] op_sel_hi:[1,0]
	v_pk_mul_f32 v[44:45], v[44:45], v[0:1] op_sel_hi:[1,0]
	v_pk_mul_f32 v[42:43], v[42:43], v[0:1] op_sel_hi:[1,0]
	v_pk_mul_f32 v[40:41], v[40:41], v[0:1] op_sel_hi:[1,0]
	v_pk_mul_f32 v[38:39], v[38:39], v[0:1] op_sel_hi:[1,0]
	v_pk_mul_f32 v[36:37], v[36:37], v[0:1] op_sel_hi:[1,0]
	v_pk_mul_f32 v[34:35], v[34:35], v[0:1] op_sel_hi:[1,0]
	v_pk_mul_f32 v[32:33], v[32:33], v[0:1] op_sel_hi:[1,0]
	v_pk_mul_f32 v[30:31], v[30:31], v[0:1] op_sel_hi:[1,0]
	v_pk_mul_f32 v[28:29], v[28:29], v[0:1] op_sel_hi:[1,0]
	v_pk_mul_f32 v[26:27], v[26:27], v[0:1] op_sel_hi:[1,0]
	v_pk_mul_f32 v[24:25], v[24:25], v[0:1] op_sel_hi:[1,0]
	v_pk_mul_f32 v[22:23], v[22:23], v[0:1] op_sel_hi:[1,0]
	v_pk_mul_f32 v[20:21], v[20:21], v[0:1] op_sel_hi:[1,0]
	v_pk_mul_f32 v[18:19], v[18:19], v[0:1] op_sel_hi:[1,0]
	v_pk_mul_f32 v[16:17], v[16:17], v[0:1] op_sel_hi:[1,0]
	v_sub_f32_e32 v80, v80, v237
	v_sub_f32_e32 v96, v96, v237
	v_sub_f32_e32 v81, v81, v237
	v_sub_f32_e32 v97, v97, v237
	v_sub_f32_e32 v82, v82, v237
	v_sub_f32_e32 v98, v98, v237
	v_sub_f32_e32 v83, v83, v237
	v_sub_f32_e32 v99, v99, v237
	v_sub_f32_e32 v84, v84, v237
	v_sub_f32_e32 v100, v100, v237
	v_sub_f32_e32 v85, v85, v237
	v_sub_f32_e32 v101, v101, v237
	v_sub_f32_e32 v86, v86, v237
	v_sub_f32_e32 v102, v102, v237
	v_sub_f32_e32 v87, v87, v237
	v_sub_f32_e32 v103, v103, v237
	v_sub_f32_e32 v88, v88, v237
	v_sub_f32_e32 v104, v104, v237
	v_sub_f32_e32 v89, v89, v237
	v_sub_f32_e32 v105, v105, v237
	v_sub_f32_e32 v90, v90, v237
	v_sub_f32_e32 v106, v106, v237
	v_sub_f32_e32 v91, v91, v237
	v_sub_f32_e32 v107, v107, v237
	v_sub_f32_e32 v92, v92, v237
	v_sub_f32_e32 v108, v108, v237
	v_sub_f32_e32 v93, v93, v237
	v_sub_f32_e32 v109, v109, v237
	v_sub_f32_e32 v94, v94, v237
	v_sub_f32_e32 v110, v110, v237
	v_sub_f32_e32 v95, v95, v237
	v_sub_f32_e32 v111, v111, v237
	v_sub_f32_e32 v216, v216, v237
	v_sub_f32_e32 v217, v217, v237
	v_sub_f32_e32 v218, v218, v237
	v_sub_f32_e32 v219, v219, v237
	v_sub_f32_e32 v220, v220, v237
	v_sub_f32_e32 v221, v221, v237
	v_sub_f32_e32 v222, v222, v237
	v_sub_f32_e32 v223, v223, v237
	v_sub_f32_e32 v224, v224, v237
	v_sub_f32_e32 v225, v225, v237
	v_sub_f32_e32 v226, v226, v237
	v_sub_f32_e32 v227, v227, v237
	v_sub_f32_e32 v228, v228, v237
	v_sub_f32_e32 v229, v229, v237
	v_sub_f32_e32 v230, v230, v237
	v_sub_f32_e32 v231, v231, v237
	s_branch .LBB0_1094
; DI unsigned pk2(float a, float b) { f32x2 f = {a, b}; bf16v2 r = __builtin_convertvector(f, bf16v2); return __builtin_bit_cast(unsigned, r); }
; #define VLD(dst, j, dt) do { LAS unsigned char* va_ = vb + (32 * (dt) + n) * VROW + (16 * (j) + 4 * g) * 2; const u32x2 lo_ = *(const LAS u32x2*)(va_), hi_ = *(const LAS u32x2*)(va_ + 16); dst = (u32x4){lo_.x, lo_.y, hi_.x, hi_.y}; } while (0)
; DI void attn_unit(LAS unsigned char* lds, int wid, int b, int h, int qb) {
;     ...
;             const float mnew = fmaxf(mrow, mx), alpha = __builtin_amdgcn_exp2f(mrow - mnew); mrow = mnew;
;             float ls = 0.f;
; #pragma unroll
;             for (int i = 0; i < 16; ++i) { s0[i] = __builtin_amdgcn_exp2f(s0[i] - mnew); s1[i] = __builtin_amdgcn_exp2f(s1[i] - mnew); ls += s0[i] + s1[i]; }
;             lrow = lrow * alpha + ls;
;             if (__builtin_amdgcn_ballot_w64(alpha != 1.f) != 0ull) {
; #pragma unroll
;                 for (int dt = 0; dt < 4; ++dt)
; #pragma unroll
;                     for (int i = 0; i < 16; ++i) o[dt][i] *= alpha;
;             }
;             bf16x8 pf[4];
; #pragma unroll
;             for (int jj = 0; jj < 2; ++jj) { u32x4 w0, w1;
;                 w0.x = pk2(s0[8 * jj + 0], s0[8 * jj + 1]); w0.y = pk2(s0[8 * jj + 2], s0[8 * jj + 3]); w0.z = pk2(s0[8 * jj + 4], s0[8 * jj + 5]); w0.w = pk2(s0[8 * jj + 6], s0[8 * jj + 7]);
;                 w1.x = pk2(s1[8 * jj + 0], s1[8 * jj + 1]); w1.y = pk2(s1[8 * jj + 2], s1[8 * jj + 3]); w1.z = pk2(s1[8 * jj + 4], s1[8 * jj + 5]); w1.w = pk2(s1[8 * jj + 6], s1[8 * jj + 7]);
;                 pf[jj] = __builtin_bit_cast(bf16x8, w0); pf[2 + jj] = __builtin_bit_cast(bf16x8, w1); }
; #pragma unroll
;             for (int j = 0; j < 4; ++j) {
;                 if (j < 3) {
; #pragma unroll
;                     for (int dt = 0; dt < 4; ++dt) VLD(vf[(j + 1) & 1][dt], j + 1, dt);
;                 }
; #pragma unroll
;                 for (int dt = 0; dt < 4; ++dt) o[dt] = __builtin_amdgcn_mfma_f32_32x32x16_bf16(__builtin_bit_cast(bf16x8, vf[j & 1][dt]), pf[j], o[dt], 0, 0, 0);
;                 __builtin_amdgcn_sched_barrier(0); }
.Lfold_2_keep:
	v_mov_b32_e32 v0, 1.0
.LBB0_1094:
	v_exp_f32_e32 v80, v80
	v_exp_f32_e32 v96, v96
	v_exp_f32_e32 v81, v81
	v_exp_f32_e32 v97, v97
	v_exp_f32_e32 v82, v82
	v_exp_f32_e32 v98, v98
	v_exp_f32_e32 v83, v83
	v_exp_f32_e32 v99, v99
	v_add_f32_e32 v208, v96, v80
	v_exp_f32_e32 v84, v84
	v_exp_f32_e32 v100, v100
	v_add_f32_e32 v208, 0, v208
	v_add_f32_e32 v209, v97, v81
	v_exp_f32_e32 v85, v85
	v_exp_f32_e32 v101, v101
	v_add_f32_e32 v208, v209, v208
	v_add_f32_e32 v209, v98, v82
	v_exp_f32_e32 v86, v86
	v_exp_f32_e32 v102, v102
	v_add_f32_e32 v208, v209, v208
	v_add_f32_e32 v209, v99, v83
	v_exp_f32_e32 v87, v87
	v_exp_f32_e32 v103, v103
	v_add_f32_e32 v208, v209, v208
	v_add_f32_e32 v209, v100, v84
	v_exp_f32_e32 v88, v88
	v_exp_f32_e32 v104, v104
	v_add_f32_e32 v208, v209, v208
	v_add_f32_e32 v209, v101, v85
	v_exp_f32_e32 v89, v89
	v_exp_f32_e32 v105, v105
	v_add_f32_e32 v208, v209, v208
	v_add_f32_e32 v209, v102, v86
	v_exp_f32_e32 v90, v90
	v_exp_f32_e32 v106, v106
	v_add_f32_e32 v208, v209, v208
	v_add_f32_e32 v209, v103, v87
	v_exp_f32_e32 v91, v91
	v_exp_f32_e32 v107, v107
	v_add_f32_e32 v208, v209, v208
	v_add_f32_e32 v209, v104, v88
	v_exp_f32_e32 v92, v92
	v_exp_f32_e32 v108, v108
	v_add_f32_e32 v208, v209, v208
	v_add_f32_e32 v209, v105, v89
	v_exp_f32_e32 v93, v93
	v_exp_f32_e32 v109, v109
	v_add_f32_e32 v208, v209, v208
	v_add_f32_e32 v209, v106, v90
	v_exp_f32_e32 v94, v94
	v_exp_f32_e32 v110, v110
	v_add_f32_e32 v208, v209, v208
	v_add_f32_e32 v209, v107, v91
	v_exp_f32_e32 v95, v95
	v_exp_f32_e32 v111, v111
	v_add_f32_e32 v208, v209, v208
	v_add_f32_e32 v209, v108, v92
	v_add_f32_e32 v208, v209, v208
	v_add_f32_e32 v209, v109, v93
	v_add_f32_e32 v208, v209, v208
	v_cvt_pk_bf16_f32 v80, v80, v81
	v_cvt_pk_bf16_f32 v81, v82, v83
	v_cvt_pk_bf16_f32 v82, v84, v85
	v_cvt_pk_bf16_f32 v83, v86, v87
	v_add_f32_e32 v84, v110, v94
	v_add_f32_e32 v84, v84, v208
	v_mfma_f32_32x32x16_bf16 v[64:79], v[168:171], v[80:83], v[64:79]
	v_add_f32_e32 v85, v111, v95
	v_add_f32_e32 v168, v85, v84
	v_cvt_pk_bf16_f32 v84, v96, v97
	v_cvt_pk_bf16_f32 v85, v98, v99
	v_cvt_pk_bf16_f32 v86, v100, v101
	v_cvt_pk_bf16_f32 v87, v102, v103
	v_cvt_pk_bf16_f32 v88, v88, v89
	v_mfma_f32_32x32x16_bf16 v[48:63], v[180:183], v[80:83], v[48:63]
	v_cvt_pk_bf16_f32 v89, v90, v91
	v_cvt_pk_bf16_f32 v90, v92, v93
	v_cvt_pk_bf16_f32 v91, v94, v95
	v_cvt_pk_bf16_f32 v92, v104, v105
	v_cvt_pk_bf16_f32 v93, v106, v107
	v_cvt_pk_bf16_f32 v94, v108, v109
	v_cvt_pk_bf16_f32 v95, v110, v111
	s_waitcnt lgkmcnt(1)
	v_mfma_f32_32x32x16_bf16 v[32:47], v[176:179], v[80:83], v[32:47]
	ds_read2_b64 v[96:99], v15 offset0:132 offset1:134
	ds_read2_b64 v[100:103], v205 offset0:164 offset1:166
	ds_read2_b64 v[104:107], v206 offset0:196 offset1:198
	ds_read2_b64 v[108:111], v207 offset0:228 offset1:230
	v_fmac_f32_e32 v168, v185, v0
	s_waitcnt lgkmcnt(4)
	v_mfma_f32_32x32x16_bf16 v[16:31], v[172:175], v[80:83], v[16:31]
	s_waitcnt lgkmcnt(3)
	v_mfma_f32_32x32x16_bf16 v[64:79], v[96:99], v[88:91], v[64:79]
	s_waitcnt lgkmcnt(2)
	v_mfma_f32_32x32x16_bf16 v[48:63], v[100:103], v[88:91], v[48:63]
	s_waitcnt lgkmcnt(1)
	v_mfma_f32_32x32x16_bf16 v[32:47], v[104:107], v[88:91], v[32:47]
	ds_read2_b64 v[80:83], v15 offset0:136 offset1:138
	ds_read2_b64 v[96:99], v205 offset0:168 offset1:170
	ds_read2_b64 v[100:103], v206 offset0:200 offset1:202
	ds_read2_b64 v[104:107], v207 offset0:232 offset1:234
	s_waitcnt lgkmcnt(4)
	v_mfma_f32_32x32x16_bf16 v[16:31], v[108:111], v[88:91], v[16:31]
	s_waitcnt lgkmcnt(3)
	v_mfma_f32_32x32x16_bf16 v[64:79], v[80:83], v[84:87], v[64:79]
	s_waitcnt lgkmcnt(2)
	v_mfma_f32_32x32x16_bf16 v[48:63], v[96:99], v[84:87], v[48:63]
	s_waitcnt lgkmcnt(1)
	v_mfma_f32_32x32x16_bf16 v[32:47], v[100:103], v[84:87], v[32:47]
	ds_read2_b64 v[80:83], v15 offset0:140 offset1:142
	ds_read2_b64 v[88:91], v205 offset0:172 offset1:174
	ds_read2_b64 v[96:99], v206 offset0:204 offset1:206
	ds_read2_b64 v[100:103], v207 offset0:236 offset1:238
	s_waitcnt lgkmcnt(4)
	v_mfma_f32_32x32x16_bf16 v[16:31], v[104:107], v[84:87], v[16:31]
	s_waitcnt lgkmcnt(3)
	v_mfma_f32_32x32x16_bf16 v[64:79], v[80:83], v[92:95], v[64:79]
	s_waitcnt lgkmcnt(2)
	v_mfma_f32_32x32x16_bf16 v[48:63], v[88:91], v[92:95], v[48:63]
	s_waitcnt lgkmcnt(1)
	v_mfma_f32_32x32x16_bf16 v[32:47], v[96:99], v[92:95], v[32:47]
	s_waitcnt lgkmcnt(0)
	v_mfma_f32_32x32x16_bf16 v[16:31], v[100:103], v[92:95], v[16:31]
	v_mov_b32_e32 v185, v168
	s_branch .LBB0_1096

; #define LAS __attribute__((address_space(3)))
; DI float shfl_xor_l(float v, int lane, int m) { return __int_as_float(__builtin_amdgcn_ds_bpermute((lane ^ m) << 2, __float_as_int(v))); }
; #define A_LOAD(kt) do { const size_t ko = (size_t)(kt) * 64; st0 = *(const u32x4*)(kn_src + ko * 2048); st1 = *(const u32x4*)(kn_src + (ko + 32) * 2048); \
;         st2 = *(const u32x4*)(kr_src + ko * 64); st3 = *(const u32x4*)(v_src + ko); st4 = *(const u32x4*)(v_src + ko + (size_t)64 * 8192); } while (0)
; #define VLD(dst, j, dt) do { LAS unsigned char* va_ = vb + (32 * (dt) + n) * VROW + (16 * (j) + 4 * g) * 2; const u32x2 lo_ = *(const LAS u32x2*)(va_), hi_ = *(const LAS u32x2*)(va_ + 16); dst = (u32x4){lo_.x, lo_.y, hi_.x, hi_.y}; } while (0)
; DI void attn_unit(LAS unsigned char* lds, int wid, int b, int h, int qb) {
;     ...
;     for (int kt = 0; kt < nkt; ++kt) {
;         const int buf = kt & 1;
;         if (kt + 1 < nkt) A_LOAD(kt + 1);
;         if (kt <= cq) {
;             LAS unsigned char* kb = lds + buf * ABUF; LAS unsigned char* vb = kb + KBYTES;
;             f32x16 s0, s1;
; #pragma unroll
;             for (int i = 0; i < 16; ++i) { s0[i] = 0.f; s1[i] = 0.f; }
;     ...
;             bf16x8 ka[3][2];
;             ka[0][0] = KLD(0, 0); ka[0][1] = KLD(0, 1); ka[1][0] = KLD(1, 0); ka[1][1] = KLD(1, 1);
; #pragma unroll
;             for (int ks = 0; ks < 12; ++ks) {
;                 if (ks + 2 < 12) { ka[(ks + 2) % 3][0] = KLD(ks + 2, 0); ka[(ks + 2) % 3][1] = KLD(ks + 2, 1); }
;                 s0 = __builtin_amdgcn_mfma_f32_32x32x16_bf16(ka[ks % 3][0], qf[ks], s0, 0, 0, 0); s1 = __builtin_amdgcn_mfma_f32_32x32x16_bf16(ka[ks % 3][1], qf[ks], s1, 0, 0, 0);
;                 __builtin_amdgcn_sched_barrier(0); }
;             u32x4 vf[2][4];
; #pragma unroll
;             for (int dt = 0; dt < 4; ++dt) VLD(vf[0][dt], 0, dt);
;             float mx = s0[0];
; #pragma unroll
;             for (int i = 1; i < 16; ++i) mx = fmaxf(mx, s0[i]);
; #pragma unroll
;             for (int i = 0; i < 16; ++i) mx = fmaxf(mx, s1[i]);
;             mx = fmaxf(mx, shfl_xor_l(mx, lane, 32));
.LBB0_1098:
	s_lshl_b32 s18, s56, 2
	s_or_b32 s18, s18, 2
	s_cmp_ge_u32 s18, s25
	s_cbranch_scc1 .LBB0_1077
	s_bitcmp1_b32 s4, 0
	s_cselect_b32 s4, 0xa800, 0
	s_add_i32 s4, s4, 0
	v_add3_u32 v0, s4, v193, v204
	ds_read_b128 v[2:5], v0
	ds_read_b128 v[6:9], v0 offset:32
	s_waitcnt lgkmcnt(1)
	v_mfma_f32_32x32x16_bf16 v[80:95], v[2:5], v[156:159], v[216:231]
	ds_read_b128 v[2:5], v0 offset:12800
	ds_read_b128 v[10:13], v0 offset:64
	ds_read_b128 v[160:163], v0 offset:12832
	ds_read_b128 v[164:167], v0 offset:12864
	s_waitcnt lgkmcnt(3)
	v_mfma_f32_32x32x16_bf16 v[96:111], v[2:5], v[156:159], v[216:231]
	v_mfma_f32_32x32x16_bf16 v[80:95], v[6:9], v[152:155], v[80:95]
	ds_read_b128 v[2:5], v0 offset:96
	ds_read_b128 v[6:9], v0 offset:12896
	s_waitcnt lgkmcnt(3)
	v_mfma_f32_32x32x16_bf16 v[96:111], v[160:163], v[152:155], v[96:111]
	v_mfma_f32_32x32x16_bf16 v[80:95], v[10:13], v[148:151], v[80:95]
	ds_read_b128 v[10:13], v0 offset:128
	ds_read_b128 v[152:155], v0 offset:12928
	s_waitcnt lgkmcnt(4)
	v_mfma_f32_32x32x16_bf16 v[96:111], v[164:167], v[148:151], v[96:111]
	s_waitcnt lgkmcnt(3)
	v_mfma_f32_32x32x16_bf16 v[80:95], v[2:5], v[144:147], v[80:95]
	ds_read_b128 v[2:5], v0 offset:160
	ds_read_b128 v[148:151], v0 offset:12960
	s_waitcnt lgkmcnt(4)
	v_mfma_f32_32x32x16_bf16 v[96:111], v[6:9], v[144:147], v[96:111]
	s_waitcnt lgkmcnt(3)
	v_mfma_f32_32x32x16_bf16 v[80:95], v[10:13], v[140:143], v[80:95]
	ds_read_b128 v[6:9], v0 offset:192
	ds_read_b128 v[10:13], v0 offset:12992
	s_waitcnt lgkmcnt(4)
	v_mfma_f32_32x32x16_bf16 v[96:111], v[152:155], v[140:143], v[96:111]
	s_waitcnt lgkmcnt(3)
	v_mfma_f32_32x32x16_bf16 v[80:95], v[2:5], v[136:139], v[80:95]
	ds_read_b128 v[2:5], v0 offset:224
	ds_read_b128 v[140:143], v0 offset:13024
	s_waitcnt lgkmcnt(4)
	v_mfma_f32_32x32x16_bf16 v[96:111], v[148:151], v[136:139], v[96:111]
	s_waitcnt lgkmcnt(3)
	v_mfma_f32_32x32x16_bf16 v[80:95], v[6:9], v[132:135], v[80:95]
	ds_read_b128 v[6:9], v0 offset:256
	ds_read_b128 v[136:139], v0 offset:13056
	s_waitcnt lgkmcnt(4)
	v_mfma_f32_32x32x16_bf16 v[96:111], v[10:13], v[132:135], v[96:111]
	s_waitcnt lgkmcnt(3)
	v_mfma_f32_32x32x16_bf16 v[80:95], v[2:5], v[128:131], v[80:95]
	ds_read_b128 v[2:5], v0 offset:288
	ds_read_b128 v[10:13], v0 offset:13088
	s_waitcnt lgkmcnt(4)
	v_mfma_f32_32x32x16_bf16 v[96:111], v[140:143], v[128:131], v[96:111]
	s_waitcnt lgkmcnt(3)
	v_mfma_f32_32x32x16_bf16 v[80:95], v[6:9], v[124:127], v[80:95]
	ds_read_b128 v[6:9], v0 offset:320
	ds_read_b128 v[128:131], v0 offset:13120
	s_waitcnt lgkmcnt(4)
	v_mfma_f32_32x32x16_bf16 v[96:111], v[136:139], v[124:127], v[96:111]
	s_waitcnt lgkmcnt(3)
	v_mfma_f32_32x32x16_bf16 v[80:95], v[2:5], v[120:123], v[80:95]
	ds_read_b128 v[2:5], v0 offset:352
	ds_read_b128 v[124:127], v0 offset:13152
	s_waitcnt lgkmcnt(4)
	v_mfma_f32_32x32x16_bf16 v[96:111], v[10:13], v[120:123], v[96:111]
	s_waitcnt lgkmcnt(3)
	v_mfma_f32_32x32x16_bf16 v[80:95], v[6:9], v[116:119], v[80:95]
	s_waitcnt lgkmcnt(2)
	v_mfma_f32_32x32x16_bf16 v[96:111], v[128:131], v[116:119], v[96:111]
	s_waitcnt lgkmcnt(1)
	v_mfma_f32_32x32x16_bf16 v[80:95], v[2:5], v[112:115], v[80:95]
	v_add_u32_e32 v0, s4, v188
	v_add_u32_e32 v6, v0, v191
	v_add_u32_e32 v15, 0x6000, v6
	v_add_u32_e32 v116, 0x7000, v6
	v_add_u32_e32 v117, 0x8000, v6
	ds_read2_b64 v[2:5], v15 offset0:128 offset1:130
	ds_read2_b64 v[10:13], v117 offset0:192 offset1:194
	s_nop 4
	v_max_f32_e32 v0, v81, v81
	v_max_f32_e32 v7, v80, v80
	v_max_f32_e32 v0, v7, v0
	s_waitcnt lgkmcnt(2)
	v_mfma_f32_32x32x16_bf16 v[96:111], v[124:127], v[112:115], v[96:111]
	v_max3_f32 v0, v0, v82, v83
	v_max3_f32 v0, v0, v84, v85
	v_max3_f32 v0, v0, v86, v87
	v_max3_f32 v0, v0, v88, v89
	v_max3_f32 v0, v0, v90, v91
	v_max3_f32 v0, v0, v92, v93
	v_max3_f32 v0, v0, v94, v95
	s_nop 4
	v_max3_f32 v0, v0, v96, v97
	v_max3_f32 v0, v0, v98, v99
	v_max3_f32 v0, v0, v100, v101
	v_max3_f32 v0, v0, v102, v103
	v_max3_f32 v0, v0, v104, v105
	v_max3_f32 v0, v0, v106, v107
	v_max3_f32 v0, v0, v108, v109
	v_max3_f32 v0, v0, v110, v111
	ds_bpermute_b32 v7, v189, v0
	ds_read2_b64 v[112:115], v116 offset0:160 offset1:162
	s_waitcnt lgkmcnt(1)
	v_max_f32_e32 v237, v0, v7
	v_add_u32_e32 v14, 0x9000, v6
	v_cmp_lt_f32_e32 vcc, 0x41000000, v237
	ds_read2_b64 v[6:9], v14 offset0:224 offset1:226
	s_cbranch_vccz .Lfold_3_keep
; DI void attn_unit(LAS unsigned char* lds, int wid, int b, int h, int qb) {
;     ...
;             const float mnew = fmaxf(mrow, mx), alpha = __builtin_amdgcn_exp2f(mrow - mnew); mrow = mnew;
;             float ls = 0.f;
; #pragma unroll
;             for (int i = 0; i < 16; ++i) { s0[i] = __builtin_amdgcn_exp2f(s0[i] - mnew); s1[i] = __builtin_amdgcn_exp2f(s1[i] - mnew); ls += s0[i] + s1[i]; }
;             lrow = lrow * alpha + ls;
;             if (__builtin_amdgcn_ballot_w64(alpha != 1.f) != 0ull) {
; #pragma unroll
;                 for (int dt = 0; dt < 4; ++dt)
; #pragma unroll
;                     for (int i = 0; i < 16; ++i) o[dt][i] *= alpha;
;             }
.Lfold_3_upd:
	v_max_f32_e32 v237, 0, v237
	v_exp_f32_e64 v0, -v237
	s_nop 0
	v_pk_mul_f32 v[78:79], v[78:79], v[0:1] op_sel_hi:[1,0]
	v_pk_mul_f32 v[76:77], v[76:77], v[0:1] op_sel_hi:[1,0]
	v_pk_mul_f32 v[74:75], v[74:75], v[0:1] op_sel_hi:[1,0]
	v_pk_mul_f32 v[72:73], v[72:73], v[0:1] op_sel_hi:[1,0]
	v_pk_mul_f32 v[70:71], v[70:71], v[0:1] op_sel_hi:[1,0]
	v_pk_mul_f32 v[68:69], v[68:69], v[0:1] op_sel_hi:[1,0]
	v_pk_mul_f32 v[66:67], v[66:67], v[0:1] op_sel_hi:[1,0]
	v_pk_mul_f32 v[64:65], v[64:65], v[0:1] op_sel_hi:[1,0]
	v_pk_mul_f32 v[62:63], v[62:63], v[0:1] op_sel_hi:[1,0]
	v_pk_mul_f32 v[60:61], v[60:61], v[0:1] op_sel_hi:[1,0]
	v_pk_mul_f32 v[58:59], v[58:59], v[0:1] op_sel_hi:[1,0]
	v_pk_mul_f32 v[56:57], v[56:57], v[0:1] op_sel_hi:[1,0]
	v_pk_mul_f32 v[54:55], v[54:55], v[0:1] op_sel_hi:[1,0]
	v_pk_mul_f32 v[52:53], v[52:53], v[0:1] op_sel_hi:[1,0]
	v_pk_mul_f32 v[50:51], v[50:51], v[0:1] op_sel_hi:[1,0]
	v_pk_mul_f32 v[48:49], v[48:49], v[0:1] op_sel_hi:[1,0]
	v_pk_mul_f32 v[46:47], v[46:47], v[0:1] op_sel_hi:[1,0]
	v_pk_mul_f32 v[44:45], v[44:45], v[0:1] op_sel_hi:[1,0]
	v_pk_mul_f32 v[42:43], v[42:43], v[0:1] op_sel_hi:[1,0]
	v_pk_mul_f32 v[40:41], v[40:41], v[0:1] op_sel_hi:[1,0]
	v_pk_mul_f32 v[38:39], v[38:39], v[0:1] op_sel_hi:[1,0]
	v_pk_mul_f32 v[36:37], v[36:37], v[0:1] op_sel_hi:[1,0]
	v_pk_mul_f32 v[34:35], v[34:35], v[0:1] op_sel_hi:[1,0]
	v_pk_mul_f32 v[32:33], v[32:33], v[0:1] op_sel_hi:[1,0]
	v_pk_mul_f32 v[30:31], v[30:31], v[0:1] op_sel_hi:[1,0]
	v_pk_mul_f32 v[28:29], v[28:29], v[0:1] op_sel_hi:[1,0]
	v_pk_mul_f32 v[26:27], v[26:27], v[0:1] op_sel_hi:[1,0]
	v_pk_mul_f32 v[24:25], v[24:25], v[0:1] op_sel_hi:[1,0]
	v_pk_mul_f32 v[22:23], v[22:23], v[0:1] op_sel_hi:[1,0]
	v_pk_mul_f32 v[20:21], v[20:21], v[0:1] op_sel_hi:[1,0]
	v_pk_mul_f32 v[18:19], v[18:19], v[0:1] op_sel_hi:[1,0]
	v_pk_mul_f32 v[16:17], v[16:17], v[0:1] op_sel_hi:[1,0]
	v_sub_f32_e32 v80, v80, v237
	v_sub_f32_e32 v96, v96, v237
	v_sub_f32_e32 v81, v81, v237
	v_sub_f32_e32 v97, v97, v237
	v_sub_f32_e32 v82, v82, v237
	v_sub_f32_e32 v98, v98, v237
	v_sub_f32_e32 v83, v83, v237
	v_sub_f32_e32 v99, v99, v237
	v_sub_f32_e32 v84, v84, v237
	v_sub_f32_e32 v100, v100, v237
	v_sub_f32_e32 v85, v85, v237
	v_sub_f32_e32 v101, v101, v237
	v_sub_f32_e32 v86, v86, v237
	v_sub_f32_e32 v102, v102, v237
	v_sub_f32_e32 v87, v87, v237
	v_sub_f32_e32 v103, v103, v237
	v_sub_f32_e32 v88, v88, v237
	v_sub_f32_e32 v104, v104, v237
	v_sub_f32_e32 v89, v89, v237
	v_sub_f32_e32 v105, v105, v237
	v_sub_f32_e32 v90, v90, v237
	v_sub_f32_e32 v106, v106, v237
	v_sub_f32_e32 v91, v91, v237
	v_sub_f32_e32 v107, v107, v237
	v_sub_f32_e32 v92, v92, v237
	v_sub_f32_e32 v108, v108, v237
	v_sub_f32_e32 v93, v93, v237
	v_sub_f32_e32 v109, v109, v237
	v_sub_f32_e32 v94, v94, v237
	v_sub_f32_e32 v110, v110, v237
	v_sub_f32_e32 v95, v95, v237
	v_sub_f32_e32 v111, v111, v237
	v_sub_f32_e32 v216, v216, v237
	v_sub_f32_e32 v217, v217, v237
	v_sub_f32_e32 v218, v218, v237
	v_sub_f32_e32 v219, v219, v237
	v_sub_f32_e32 v220, v220, v237
	v_sub_f32_e32 v221, v221, v237
	v_sub_f32_e32 v222, v222, v237
	v_sub_f32_e32 v223, v223, v237
	v_sub_f32_e32 v224, v224, v237
	v_sub_f32_e32 v225, v225, v237
	v_sub_f32_e32 v226, v226, v237
	v_sub_f32_e32 v227, v227, v237
	v_sub_f32_e32 v228, v228, v237
	v_sub_f32_e32 v229, v229, v237
	v_sub_f32_e32 v230, v230, v237
	v_sub_f32_e32 v231, v231, v237
	s_branch .LBB0_1076
.Lfold_3_keep:
	v_mov_b32_e32 v0, 1.0
	s_branch .LBB0_1076
